# v15 plus: packed f32 add/mul/fma inside the three flash-style softmax loops split into scalar pairs
# speedup vs baseline: 1.0048x; 1.0016x over previous
.LBB0_2290:
	s_mul_i32 s4, s20, 0x4700
	s_addk_i32 s4, 0x100
	v_add3_u32 v112, s4, v120, v122
	ds_read_b128 v[34:37], v112 offset:4608
	ds_read_b128 v[38:41], v112
	ds_read_b128 v[104:107], v112 offset:32
	ds_read_b128 v[108:111], v112 offset:4640
	s_add_i32 s5, s2, 63
	s_cmp_le_i32 s5, s0
	s_waitcnt lgkmcnt(2)
	v_mfma_f32_32x32x16_bf16 v[50:65], v[38:41], v[66:69], 0
	v_mfma_f32_32x32x16_bf16 v[34:49], v[34:37], v[66:69], 0
	s_waitcnt lgkmcnt(1)
	v_mfma_f32_32x32x16_bf16 v[50:65], v[104:107], v[70:73], v[50:65]
	s_waitcnt lgkmcnt(0)
	v_mfma_f32_32x32x16_bf16 v[34:49], v[108:111], v[70:73], v[34:49]
	ds_read_b128 v[104:107], v112 offset:64
	ds_read_b128 v[108:111], v112 offset:4672
	s_waitcnt lgkmcnt(1)
	v_mfma_f32_32x32x16_bf16 v[50:65], v[104:107], v[74:77], v[50:65]
	s_waitcnt lgkmcnt(0)
	v_mfma_f32_32x32x16_bf16 v[34:49], v[108:111], v[74:77], v[34:49]
	ds_read_b128 v[104:107], v112 offset:96
	ds_read_b128 v[108:111], v112 offset:4704
	s_waitcnt lgkmcnt(1)
	v_mfma_f32_32x32x16_bf16 v[50:65], v[104:107], v[78:81], v[50:65]
	v_lshl_add_u32 v104, v98, 2, s4
	s_waitcnt lgkmcnt(0)
	v_mfma_f32_32x32x16_bf16 v[34:49], v[108:111], v[78:81], v[34:49]
	ds_read_b128 v[126:129], v104 offset:18048
	ds_read_b128 v[106:109], v104 offset:17920
	ds_read_b128 v[110:113], v104 offset:17952
	ds_read_b128 v[130:133], v104 offset:18080
	ds_read_b128 v[134:137], v104 offset:17984
	ds_read_b128 v[138:141], v104 offset:18112
	ds_read_b128 v[142:145], v104 offset:18016
	ds_read_b128 v[150:153], v104 offset:18144
	s_waitcnt lgkmcnt(5)
	v_add_f32_e32 v104, v56, v112
	v_add_f32_e32 v105, v57, v113
	s_waitcnt lgkmcnt(3)
	v_add_f32_e32 v60, v60, v136
	v_add_f32_e32 v61, v61, v137
	v_add_f32_e32 v58, v58, v134
	v_add_f32_e32 v59, v59, v135
	s_waitcnt lgkmcnt(1)
	v_add_f32_e32 v64, v64, v144
	v_add_f32_e32 v65, v65, v145
	v_add_f32_e32 v62, v62, v142
	v_add_f32_e32 v63, v63, v143
	v_add_f32_e32 v54, v54, v110
	v_add_f32_e32 v55, v55, v111
	v_add_f32_e32 v52, v52, v108
	v_add_f32_e32 v53, v53, v109
	v_add_f32_e32 v110, v50, v106
	v_add_f32_e32 v111, v51, v107
	s_waitcnt lgkmcnt(0)
	v_add_f32_e32 v50, v48, v152
	v_add_f32_e32 v51, v49, v153
	v_add_f32_e32 v56, v46, v150
	v_add_f32_e32 v57, v47, v151
	v_add_f32_e32 v106, v44, v140
	v_add_f32_e32 v107, v45, v141
	v_add_f32_e32 v108, v42, v138
	v_add_f32_e32 v109, v43, v139
	v_add_f32_e32 v112, v40, v132
	v_add_f32_e32 v113, v41, v133
	v_add_f32_e32 v38, v38, v130
	v_add_f32_e32 v39, v39, v131
	v_add_f32_e32 v42, v36, v128
	v_add_f32_e32 v43, v37, v129
	v_add_f32_e32 v36, v34, v126
	v_add_f32_e32 v37, v35, v127
	s_cbranch_scc1 .LBB0_2292
	v_add_u32_e32 v34, s2, v98
	v_add_u32_e32 v35, 32, v34
	v_cmp_le_i32_e32 vcc, v35, v96
	v_add_u32_e32 v35, 33, v34
	s_nop 0
	v_cndmask_b32_e32 v36, v216, v36, vcc
	v_cmp_lt_i32_e32 vcc, v34, v96
	s_nop 1
	v_cndmask_b32_e32 v111, v216, v111, vcc
	v_cmp_le_i32_e32 vcc, v34, v96
	s_nop 1
	v_cndmask_b32_e32 v110, v216, v110, vcc
	v_cmp_le_i32_e32 vcc, v35, v96
	v_add_u32_e32 v35, 2, v34
	s_nop 0
	v_cndmask_b32_e32 v37, v216, v37, vcc
	v_cmp_le_i32_e32 vcc, v35, v96
	v_add_u32_e32 v35, 34, v34
	s_nop 0
	v_cndmask_b32_e32 v52, v216, v52, vcc
	v_cmp_le_i32_e32 vcc, v35, v96
	v_add_u32_e32 v35, 3, v34
	s_nop 0
	v_cndmask_b32_e32 v42, v216, v42, vcc
	v_cmp_le_i32_e32 vcc, v35, v96
	v_add_u32_e32 v35, 35, v34
	s_nop 0
	v_cndmask_b32_e32 v53, v216, v53, vcc
	v_cmp_le_i32_e32 vcc, v35, v96
	v_add_u32_e32 v35, 8, v34
	s_nop 0
	v_cndmask_b32_e32 v43, v216, v43, vcc
	v_cmp_le_i32_e32 vcc, v35, v96
	v_add_u32_e32 v35, 40, v34
	s_nop 0
	v_cndmask_b32_e32 v54, v216, v54, vcc
	v_cmp_le_i32_e32 vcc, v35, v96
	v_add_u32_e32 v35, 9, v34
	s_nop 0
	v_cndmask_b32_e32 v38, v216, v38, vcc
	v_cmp_le_i32_e32 vcc, v35, v96
	v_add_u32_e32 v35, 41, v34
	s_nop 0
	v_cndmask_b32_e32 v55, v216, v55, vcc
	v_cmp_le_i32_e32 vcc, v35, v96
	v_add_u32_e32 v35, 10, v34
	s_nop 0
	v_cndmask_b32_e32 v39, v216, v39, vcc
	v_cmp_le_i32_e32 vcc, v35, v96
	v_add_u32_e32 v35, 42, v34
	s_nop 0
	v_cndmask_b32_e32 v104, v216, v104, vcc
	v_cmp_le_i32_e32 vcc, v35, v96
	v_add_u32_e32 v35, 11, v34
	s_nop 0
	v_cndmask_b32_e32 v112, v216, v112, vcc
	v_cmp_le_i32_e32 vcc, v35, v96
	v_add_u32_e32 v35, 43, v34
	s_nop 0
	v_cndmask_b32_e32 v105, v216, v105, vcc
	v_cmp_le_i32_e32 vcc, v35, v96
	v_add_u32_e32 v35, 16, v34
	s_nop 0
	v_cndmask_b32_e32 v113, v216, v113, vcc
	v_cmp_le_i32_e32 vcc, v35, v96
	v_add_u32_e32 v35, 48, v34
	s_nop 0
	v_cndmask_b32_e32 v58, v216, v58, vcc
	v_cmp_le_i32_e32 vcc, v35, v96
	v_add_u32_e32 v35, 17, v34
	s_nop 0
	v_cndmask_b32_e32 v108, v216, v108, vcc
	v_cmp_le_i32_e32 vcc, v35, v96
	v_add_u32_e32 v35, 49, v34
	s_nop 0
	v_cndmask_b32_e32 v59, v216, v59, vcc
	v_cmp_le_i32_e32 vcc, v35, v96
	v_add_u32_e32 v35, 18, v34
	s_nop 0
	v_cndmask_b32_e32 v109, v216, v109, vcc
	v_cmp_le_i32_e32 vcc, v35, v96
	v_add_u32_e32 v35, 50, v34
	s_nop 0
	v_cndmask_b32_e32 v60, v216, v60, vcc
	v_cmp_le_i32_e32 vcc, v35, v96
	v_add_u32_e32 v35, 19, v34
	s_nop 0
	v_cndmask_b32_e32 v106, v216, v106, vcc
	v_cmp_le_i32_e32 vcc, v35, v96
	v_add_u32_e32 v35, 51, v34
	s_nop 0
	v_cndmask_b32_e32 v61, v216, v61, vcc
	v_cmp_le_i32_e32 vcc, v35, v96
	v_add_u32_e32 v35, 24, v34
	s_nop 0
	v_cndmask_b32_e32 v107, v216, v107, vcc
	v_cmp_le_i32_e32 vcc, v35, v96
	v_add_u32_e32 v35, 56, v34
	s_nop 0
	v_cndmask_b32_e32 v62, v216, v62, vcc
	v_cmp_le_i32_e32 vcc, v35, v96
	v_add_u32_e32 v35, 25, v34
	s_nop 0
	v_cndmask_b32_e32 v56, v216, v56, vcc
	v_cmp_le_i32_e32 vcc, v35, v96
	v_add_u32_e32 v35, 57, v34
	s_nop 0
	v_cndmask_b32_e32 v63, v216, v63, vcc
	v_cmp_le_i32_e32 vcc, v35, v96
	v_add_u32_e32 v35, 26, v34
	s_nop 0
	v_cndmask_b32_e32 v57, v216, v57, vcc
	v_cmp_le_i32_e32 vcc, v35, v96
	v_add_u32_e32 v35, 58, v34
	s_nop 0
	v_cndmask_b32_e32 v64, v216, v64, vcc
	v_cmp_le_i32_e32 vcc, v35, v96
	v_add_u32_e32 v35, 27, v34
	v_add_u32_e32 v34, 59, v34
	v_cndmask_b32_e32 v50, v216, v50, vcc
	v_cmp_le_i32_e32 vcc, v35, v96
	s_nop 1
	v_cndmask_b32_e32 v65, v216, v65, vcc
	v_cmp_le_i32_e32 vcc, v34, v96
	s_nop 1
	v_cndmask_b32_e32 v51, v216, v51, vcc
.LBB0_2292:
	v_max3_f32 v34, v110, v111, v52
	v_max3_f32 v35, v36, v37, v42
	s_nop 0
	v_max3_f32 v34, v34, v53, v54
	v_max3_f32 v35, v35, v43, v38
	s_nop 0
	v_max3_f32 v34, v34, v55, v104
	v_max3_f32 v35, v35, v39, v112
	s_nop 0
	v_max3_f32 v34, v34, v105, v58
	v_max3_f32 v35, v35, v113, v108
	s_nop 0
	v_max3_f32 v34, v34, v59, v60
	v_max3_f32 v35, v35, v109, v106
	s_nop 0
	v_max3_f32 v34, v34, v61, v62
	v_max3_f32 v35, v35, v107, v56
	s_nop 0
	v_max3_f32 v34, v34, v63, v64
	v_max3_f32 v35, v35, v57, v50
	s_nop 0
	v_max3_f32 v34, v34, v35, v65
	s_nop 0
	v_max_f32_e32 v34, v34, v51
	ds_bpermute_b32 v35, v97, v34
	s_waitcnt lgkmcnt(0)
	v_max_f32_e32 v34, v34, v35
	s_nop 0
	v_max_f32_e32 v123, v124, v34
	s_nop 0
	v_cmp_neq_f32_e32 vcc, s39, v123
	s_nop 1
	v_cndmask_b32_e32 v41, 0, v123, vcc
	v_sub_f32_e32 v34, v110, v41
	v_sub_f32_e32 v38, v38, v41
	v_exp_f32_e32 v110, v34
	v_sub_f32_e32 v34, v36, v41
	v_sub_f32_e32 v36, v52, v41
	v_exp_f32_e32 v127, v38
	v_sub_f32_e32 v38, v55, v41
	v_sub_f32_e32 v45, v124, v41
	v_exp_f32_e32 v124, v34
	v_sub_f32_e32 v34, v111, v41
	v_exp_f32_e32 v111, v36
	v_sub_f32_e32 v36, v42, v41
	v_sub_f32_e32 v42, v54, v41
	v_exp_f32_e32 v48, v38
	v_sub_f32_e32 v38, v39, v41
	v_exp_f32_e32 v126, v42
	v_exp_f32_e32 v42, v38
	v_sub_f32_e32 v38, v104, v41
	v_exp_f32_e32 v128, v38
	v_sub_f32_e32 v38, v112, v41
	v_exp_f32_e32 v112, v38
	v_sub_f32_e32 v38, v105, v41
	v_exp_f32_e32 v54, v38
	v_sub_f32_e32 v38, v113, v41
	v_exp_f32_e32 v46, v38
	v_sub_f32_e32 v38, v58, v41
	v_exp_f32_e32 v113, v38
	v_sub_f32_e32 v38, v108, v41
	v_exp_f32_e32 v129, v38
	v_sub_f32_e32 v38, v59, v41
	v_exp_f32_e32 v104, v38
	v_sub_f32_e32 v38, v109, v41
	v_exp_f32_e32 v52, v38
	v_sub_f32_e32 v38, v60, v41
	v_exp_f32_e32 v130, v38
	v_sub_f32_e32 v38, v106, v41
	v_exp_f32_e32 v131, v38
	v_sub_f32_e32 v38, v61, v41
	v_exp_f32_e32 v106, v38
	v_sub_f32_e32 v38, v107, v41
	v_exp_f32_e32 v58, v38
	v_sub_f32_e32 v38, v62, v41
	v_exp_f32_e32 v132, v38
	v_sub_f32_e32 v38, v56, v41
	v_exp_f32_e32 v133, v38
	v_sub_f32_e32 v38, v63, v41
	v_exp_f32_e32 v40, v34
	v_sub_f32_e32 v34, v37, v41
	v_exp_f32_e32 v62, v38
	v_sub_f32_e32 v38, v57, v41
	v_exp_f32_e32 v34, v34
	v_exp_f32_e32 v60, v38
	v_sub_f32_e32 v38, v64, v41
	v_exp_f32_e32 v125, v36
	v_sub_f32_e32 v36, v53, v41
	v_exp_f32_e32 v134, v38
	v_sub_f32_e32 v38, v50, v41
	v_exp_f32_e32 v44, v36
	v_sub_f32_e32 v36, v43, v41
	v_exp_f32_e32 v135, v38
	v_sub_f32_e32 v38, v65, v41
	v_add_f32_e32 v35, v124, v110
	v_exp_f32_e32 v36, v36
	v_exp_f32_e32 v50, v38
	v_sub_f32_e32 v38, v51, v41
	v_mov_b32_e32 v41, v149
	v_add_f32_e32 v64, v34, v40
	v_add_f32_e32 v65, v35, v41
	v_add_f32_e32 v37, v125, v111
	v_add_f32_e32 v65, v64, v65
	v_add_f32_e32 v64, v64, v64
	v_exp_f32_e32 v56, v38
	v_exp_f32_e32 v38, v45
	v_mov_b32_e32 v45, v65
	v_add_f32_e32 v64, v36, v44
	v_add_f32_e32 v65, v37, v45
	v_add_f32_e32 v43, v127, v126
	v_add_f32_e32 v65, v64, v65
	v_add_f32_e32 v64, v64, v64
	v_mov_b32_e32 v49, v65
	v_add_f32_e32 v64, v42, v48
	v_add_f32_e32 v65, v43, v49
	v_add_f32_e32 v47, v112, v128
	v_add_f32_e32 v65, v64, v65
	v_add_f32_e32 v64, v64, v64
	v_mov_b32_e32 v55, v65
	v_add_f32_e32 v64, v46, v54
	v_add_f32_e32 v65, v47, v55
	v_add_f32_e32 v53, v129, v113
	v_add_f32_e32 v65, v64, v65
	v_add_f32_e32 v64, v64, v64
	v_mov_b32_e32 v105, v65
	v_add_f32_e32 v64, v52, v104
	v_add_f32_e32 v65, v53, v105
	v_add_f32_e32 v59, v131, v130
	v_add_f32_e32 v65, v64, v65
	v_add_f32_e32 v64, v64, v64
	v_mov_b32_e32 v107, v65
	v_add_f32_e32 v64, v58, v106
	v_add_f32_e32 v65, v59, v107
	v_add_f32_e32 v61, v133, v132
	v_add_f32_e32 v65, v64, v65
	v_add_f32_e32 v64, v64, v64
	v_mov_b32_e32 v63, v65
	v_add_f32_e32 v64, v60, v62
	v_add_f32_e32 v65, v61, v63
	v_cvt_pk_bf16_f32 v108, v110, v40
	v_cvt_pk_bf16_f32 v109, v111, v44
	v_lshlrev_b32_e32 v44, 1, v98
	v_add_f32_e32 v65, v64, v65
	v_add_f32_e32 v64, v64, v64
	v_add_f32_e32 v57, v135, v134
	v_mov_b32_e32 v51, v65
	v_cvt_pk_bf16_f32 v110, v126, v48
	v_cvt_pk_bf16_f32 v111, v128, v54
	v_cvt_pk_bf16_f32 v104, v113, v104
	v_cvt_pk_bf16_f32 v105, v130, v106
	v_cvt_pk_bf16_f32 v106, v132, v62
	v_cvt_pk_bf16_f32 v107, v134, v50
	v_cvt_pk_bf16_f32 v40, v124, v34
	v_cvt_pk_bf16_f32 v41, v125, v36
	v_cvt_pk_bf16_f32 v42, v127, v42
	v_cvt_pk_bf16_f32 v43, v112, v46
	v_cvt_pk_bf16_f32 v34, v129, v52
	v_add3_u32 v52, s4, v121, v44
	v_add_f32_e32 v64, v56, v50
	v_add_f32_e32 v65, v57, v51
	v_cvt_pk_bf16_f32 v35, v131, v58
	v_cvt_pk_bf16_f32 v36, v133, v60
	v_cvt_pk_bf16_f32 v37, v135, v56
	v_add_u32_e32 v56, 0x2000, v52
	v_add_u32_e32 v57, 0x3000, v52
	ds_read2_b64 v[44:47], v56 offset0:128 offset1:130
	ds_read2_b64 v[48:51], v56 offset0:132 offset1:134
	ds_read2_b64 v[52:55], v57 offset0:160 offset1:162
	v_mul_f32_e32 v16, v16, v38
	v_mul_f32_e32 v17, v17, v38
	v_mul_f32_e32 v14, v14, v38
	v_mul_f32_e32 v15, v15, v38
	v_mul_f32_e32 v12, v12, v38
	v_mul_f32_e32 v13, v13, v38
	v_mul_f32_e32 v10, v10, v38
	v_mul_f32_e32 v11, v11, v38
	v_mul_f32_e32 v8, v8, v38
	v_mul_f32_e32 v9, v9, v38
	v_mul_f32_e32 v6, v6, v38
	v_mul_f32_e32 v7, v7, v38
	v_mul_f32_e32 v4, v4, v38
	v_mul_f32_e32 v5, v5, v38
	v_mul_f32_e32 v2, v2, v38
	v_mul_f32_e32 v3, v3, v38
	v_mul_f32_e32 v32, v32, v38
	v_mul_f32_e32 v33, v33, v38
	v_mul_f32_e32 v30, v30, v38
	v_mul_f32_e32 v31, v31, v38
	v_mul_f32_e32 v28, v28, v38
	v_mul_f32_e32 v29, v29, v38
	v_mul_f32_e32 v26, v26, v38
	v_mul_f32_e32 v27, v27, v38
	v_mul_f32_e32 v24, v24, v38
	v_mul_f32_e32 v25, v25, v38
	v_mul_f32_e32 v22, v22, v38
	v_mul_f32_e32 v23, v23, v38
	v_mul_f32_e32 v20, v20, v38
	v_mul_f32_e32 v21, v21, v38
	v_mul_f32_e32 v18, v18, v38
	v_mul_f32_e32 v19, v19, v38
	s_waitcnt lgkmcnt(2)
	v_mfma_f32_32x32x16_bf16 v[2:17], v[44:47], v[108:111], v[2:17]
	ds_read2_b64 v[44:47], v57 offset0:164 offset1:166
	v_add_f32_e32 v39, v64, v65
	v_fmac_f32_e32 v39, v115, v38
	v_mov_b32_e32 v124, v123
	v_mov_b32_e32 v115, v39
	s_waitcnt lgkmcnt(1)
	v_mfma_f32_32x32x16_bf16 v[18:33], v[52:55], v[108:111], v[18:33]
	v_mfma_f32_32x32x16_bf16 v[2:17], v[48:51], v[104:107], v[2:17]
	s_waitcnt lgkmcnt(0)
	v_mfma_f32_32x32x16_bf16 v[18:33], v[44:47], v[104:107], v[18:33]
	ds_read2_b64 v[44:47], v56 offset0:136 offset1:138
	ds_read2_b64 v[48:51], v57 offset0:168 offset1:170
	s_waitcnt lgkmcnt(1)
	v_mfma_f32_32x32x16_bf16 v[2:17], v[44:47], v[40:43], v[2:17]
	s_waitcnt lgkmcnt(0)
	v_mfma_f32_32x32x16_bf16 v[18:33], v[48:51], v[40:43], v[18:33]
	ds_read2_b64 v[40:43], v56 offset0:140 offset1:142
	ds_read2_b64 v[44:47], v57 offset0:172 offset1:174
	s_waitcnt lgkmcnt(1)
	v_mfma_f32_32x32x16_bf16 v[2:17], v[40:43], v[34:37], v[2:17]
	s_waitcnt lgkmcnt(0)
	v_mfma_f32_32x32x16_bf16 v[18:33], v[44:47], v[34:37], v[18:33]
	s_andn2_b64 vcc, exec, s[14:15]
	s_xor_b32 s20, s20, 1
	s_cbranch_vccnz .LBB0_2283

.LBB0_2327:
	v_max3_f32 v170, v50, v51, v52
	v_max3_f32 v171, v34, v35, v36
	v_and_b32_e32 v212, 64, v217
	v_max3_f32 v170, v170, v53, v54
	v_max3_f32 v171, v171, v37, v38
	v_add_u32_e32 v212, 64, v212
	v_max3_f32 v170, v170, v55, v56
	v_max3_f32 v171, v171, v39, v40
	ds_write_b128 v167, v[94:97]
	s_waitcnt vmcnt(6)
	ds_write_b128 v167, v[106:109] offset:1152
	s_waitcnt vmcnt(5)
	ds_write_b128 v167, v[122:125] offset:2304
	s_waitcnt vmcnt(4)
	ds_write_b128 v167, v[126:129] offset:3456
	s_waitcnt vmcnt(3)
	ds_write_b128 v167, v[130:133] offset:4608
	v_max3_f32 v170, v170, v57, v58
	v_max3_f32 v171, v171, v41, v42
	s_waitcnt vmcnt(2)
	ds_write_b128 v167, v[134:137] offset:5760
	s_waitcnt vmcnt(1)
	ds_write_b128 v167, v[138:141] offset:6912
	s_waitcnt vmcnt(0)
	ds_write_b128 v167, v[142:145] offset:8064
	v_max3_f32 v170, v170, v59, v60
	v_max3_f32 v171, v171, v43, v44
	s_waitcnt lgkmcnt(0)
	s_mov_b64 s[20:21], 0x480
	v_max3_f32 v170, v170, v61, v62
	v_max3_f32 v171, v171, v45, v46
	s_nop 0
	v_max3_f32 v170, v170, v63, v64
	v_max3_f32 v171, v171, v47, v48
	s_nop 0
	v_max3_f32 v170, v170, v171, v65
	v_xor_b32_e32 v171, 32, v217
	v_cmp_lt_i32_e32 vcc, v171, v212
	v_max_f32_e32 v170, v170, v49
	s_nop 1
	v_cndmask_b32_e32 v171, v217, v171, vcc
	v_lshlrev_b32_e32 v227, 2, v171
	ds_bpermute_b32 v171, v227, v170
	s_waitcnt lgkmcnt(0)
	v_max_f32_e32 v170, v170, v171
	s_nop 0
	v_max_f32_e32 v212, v228, v170
	s_nop 0
	v_sub_f32_e32 v34, v34, v212
	v_sub_f32_e32 v170, v228, v212
	v_exp_f32_e32 v228, v34
	v_sub_f32_e32 v34, v51, v212
	v_exp_f32_e32 v51, v34
	v_sub_f32_e32 v34, v35, v212
	v_exp_f32_e32 v35, v34
	v_sub_f32_e32 v34, v52, v212
	v_exp_f32_e32 v52, v34
	v_sub_f32_e32 v34, v36, v212
	v_exp_f32_e32 v36, v34
	v_sub_f32_e32 v34, v53, v212
	v_exp_f32_e32 v53, v34
	v_sub_f32_e32 v34, v37, v212
	v_exp_f32_e32 v37, v34
	v_sub_f32_e32 v34, v54, v212
	v_exp_f32_e32 v54, v34
	v_sub_f32_e32 v34, v38, v212
	v_exp_f32_e32 v38, v34
	v_sub_f32_e32 v34, v55, v212
	v_exp_f32_e32 v55, v34
	v_sub_f32_e32 v34, v39, v212
	v_exp_f32_e32 v39, v34
	v_sub_f32_e32 v34, v56, v212
	v_exp_f32_e32 v56, v34
	v_sub_f32_e32 v34, v40, v212
	v_exp_f32_e32 v40, v34
	v_sub_f32_e32 v34, v57, v212
	v_exp_f32_e32 v57, v34
	v_sub_f32_e32 v34, v41, v212
	v_exp_f32_e32 v41, v34
	v_sub_f32_e32 v34, v58, v212
	v_exp_f32_e32 v58, v34
	v_sub_f32_e32 v34, v42, v212
	v_exp_f32_e32 v42, v34
	v_sub_f32_e32 v34, v59, v212
	v_exp_f32_e32 v59, v34
	v_sub_f32_e32 v34, v43, v212
	v_exp_f32_e32 v43, v34
	v_sub_f32_e32 v34, v60, v212
	v_exp_f32_e32 v60, v34
	v_sub_f32_e32 v34, v44, v212
	v_exp_f32_e32 v44, v34
	v_sub_f32_e32 v34, v61, v212
	v_exp_f32_e32 v61, v34
	v_sub_f32_e32 v34, v45, v212
	v_exp_f32_e32 v45, v34
	v_sub_f32_e32 v34, v62, v212
	v_exp_f32_e32 v62, v34
	v_sub_f32_e32 v34, v46, v212
	v_exp_f32_e32 v46, v34
	v_sub_f32_e32 v34, v63, v212
	v_exp_f32_e32 v63, v34
	v_sub_f32_e32 v34, v47, v212
	v_exp_f32_e32 v47, v34
	v_sub_f32_e32 v34, v64, v212
	v_sub_f32_e32 v50, v50, v212
	v_exp_f32_e32 v64, v34
	v_sub_f32_e32 v34, v48, v212
	v_sub_f32_e32 v65, v65, v212
	v_sub_f32_e32 v49, v49, v212
	v_exp_f32_e32 v50, v50
	v_exp_f32_e32 v48, v34
	v_exp_f32_e32 v34, v170
	v_exp_f32_e32 v65, v65
	v_exp_f32_e32 v49, v49
	v_cvt_pk_bf16_f32 v230, v50, v51
	v_cvt_pk_bf16_f32 v231, v52, v53
	v_cvt_pk_bf16_f32 v232, v54, v55
	v_cvt_pk_bf16_f32 v233, v56, v57
	v_cvt_pk_bf16_f32 v234, v58, v59
	v_cvt_pk_bf16_f32 v235, v60, v61
	v_cvt_pk_bf16_f32 v236, v62, v63
	v_cvt_pk_bf16_f32 v237, v64, v65
	v_cvt_pk_bf16_f32 v238, v228, v35
	v_cvt_pk_bf16_f32 v239, v36, v37
	v_cvt_pk_bf16_f32 v240, v38, v39
	v_cvt_pk_bf16_f32 v241, v40, v41
	v_cvt_pk_bf16_f32 v242, v42, v43
	v_cvt_pk_bf16_f32 v243, v44, v45
	v_cvt_pk_bf16_f32 v244, v46, v47
	v_cvt_pk_bf16_f32 v245, v48, v49
	v_mov_b64_e32 v[170:171], v[218:219]
	v_mul_f32_e32 v16, v16, v34
	v_mul_f32_e32 v17, v17, v34
	v_cmp_ne_u64_e32 vcc, 0, v[170:171]
	v_lshl_add_u64 v[246:247], v[170:171], 0, s[20:21]
	v_lshl_add_u64 v[250:251], v[170:171], 0, 64
	v_cndmask_b32_e32 v248, -1, v170, vcc
	v_cmp_ne_u64_e32 vcc, 0, v[246:247]
	s_mov_b64 s[20:21], 0x4c0
	v_mul_f32_e32 v14, v14, v34
	v_mul_f32_e32 v15, v15, v34
	v_cndmask_b32_e32 v249, -1, v246, vcc
	v_cmp_ne_u64_e32 vcc, 0, v[250:251]
	ds_read_b64_tr_b16 v[246:247], v248
	ds_read_b64_tr_b16 v[248:249], v249
	v_cndmask_b32_e32 v252, -1, v250, vcc
	v_lshl_add_u64 v[250:251], v[170:171], 0, s[20:21]
	v_cmp_ne_u64_e32 vcc, 0, v[250:251]
	v_mul_f32_e32 v12, v12, v34
	v_mul_f32_e32 v13, v13, v34
	v_mul_f32_e32 v10, v10, v34
	v_mul_f32_e32 v11, v11, v34
	v_cndmask_b32_e32 v253, -1, v250, vcc
	ds_read_b64_tr_b16 v[250:251], v252
	ds_read_b64_tr_b16 v[252:253], v253
	v_mul_f32_e32 v8, v8, v34
	v_mul_f32_e32 v9, v9, v34
	v_mul_f32_e32 v6, v6, v34
	v_mul_f32_e32 v7, v7, v34
	v_mul_f32_e32 v4, v4, v34
	v_mul_f32_e32 v5, v5, v34
	v_mul_f32_e32 v2, v2, v34
	v_mul_f32_e32 v3, v3, v34
	v_mul_f32_e32 v32, v32, v34
	v_mul_f32_e32 v33, v33, v34
	v_mul_f32_e32 v30, v30, v34
	v_mul_f32_e32 v31, v31, v34
	v_mul_f32_e32 v28, v28, v34
	v_mul_f32_e32 v29, v29, v34
	v_mul_f32_e32 v26, v26, v34
	v_mul_f32_e32 v27, v27, v34
	v_mul_f32_e32 v24, v24, v34
	v_mul_f32_e32 v25, v25, v34
	v_mul_f32_e32 v22, v22, v34
	v_mul_f32_e32 v23, v23, v34
	v_mul_f32_e32 v20, v20, v34
	v_mul_f32_e32 v21, v21, v34
	v_mul_f32_e32 v18, v18, v34
	v_mul_f32_e32 v19, v19, v34
	s_waitcnt lgkmcnt(2)
	v_mfma_f32_32x32x16_bf16 v[2:17], v[246:249], v[230:233], v[2:17]
	s_mov_b64 s[20:21], 0xd80
	v_lshl_add_u64 v[246:247], v[170:171], 0, s[92:93]
	s_waitcnt lgkmcnt(0)
	v_mfma_f32_32x32x16_bf16 v[18:33], v[250:253], v[230:233], v[18:33]
	v_lshl_add_u64 v[230:231], v[170:171], 0, s[90:91]
	v_cmp_ne_u64_e32 vcc, 0, v[230:231]
	s_nop 1
	v_cndmask_b32_e32 v232, -1, v230, vcc
	v_lshl_add_u64 v[230:231], v[170:171], 0, s[20:21]
	v_cmp_ne_u64_e32 vcc, 0, v[230:231]
	s_mov_b64 s[20:21], 0xdc0
	s_nop 0
	v_cndmask_b32_e32 v233, -1, v230, vcc
	v_cmp_ne_u64_e32 vcc, 0, v[246:247]
	ds_read_b64_tr_b16 v[230:231], v232
	ds_read_b64_tr_b16 v[232:233], v233
	v_cndmask_b32_e32 v248, -1, v246, vcc
	v_lshl_add_u64 v[246:247], v[170:171], 0, s[20:21]
	v_cmp_ne_u64_e32 vcc, 0, v[246:247]
	s_waitcnt lgkmcnt(0)
	v_mfma_f32_32x32x16_bf16 v[2:17], v[230:233], v[234:237], v[2:17]
	v_cndmask_b32_e32 v249, -1, v246, vcc
	ds_read_b64_tr_b16 v[246:247], v248
	ds_read_b64_tr_b16 v[248:249], v249
	v_lshl_add_u64 v[230:231], v[170:171], 0, s[96:97]
	v_cmp_ne_u64_e32 vcc, 0, v[230:231]
	s_mov_b64 s[20:21], 0x1680
	s_nop 0
	v_cndmask_b32_e32 v232, -1, v230, vcc
	v_lshl_add_u64 v[230:231], v[170:171], 0, s[20:21]
	s_waitcnt lgkmcnt(0)
	v_mfma_f32_32x32x16_bf16 v[18:33], v[246:249], v[234:237], v[18:33]
	v_cmp_ne_u64_e32 vcc, 0, v[230:231]
	v_lshl_add_u64 v[234:235], v[170:171], 0, s[68:69]
	s_mov_b64 s[20:21], 0x16c0
	v_cndmask_b32_e32 v233, -1, v230, vcc
	v_cmp_ne_u64_e32 vcc, 0, v[234:235]
	ds_read_b64_tr_b16 v[230:231], v232
	ds_read_b64_tr_b16 v[232:233], v233
	v_cndmask_b32_e32 v236, -1, v234, vcc
	v_lshl_add_u64 v[234:235], v[170:171], 0, s[20:21]
	v_cmp_ne_u64_e32 vcc, 0, v[234:235]
	s_waitcnt lgkmcnt(0)
	v_mfma_f32_32x32x16_bf16 v[2:17], v[230:233], v[238:241], v[2:17]
	v_cndmask_b32_e32 v237, -1, v234, vcc
	ds_read_b64_tr_b16 v[234:235], v236
	ds_read_b64_tr_b16 v[236:237], v237
	v_lshl_add_u64 v[230:231], v[170:171], 0, s[78:79]
	v_cmp_ne_u64_e32 vcc, 0, v[230:231]
	s_mov_b64 s[20:21], 0x1f80
	s_nop 0
	v_cndmask_b32_e32 v232, -1, v230, vcc
	v_lshl_add_u64 v[230:231], v[170:171], 0, s[20:21]
	s_waitcnt lgkmcnt(0)
	v_mfma_f32_32x32x16_bf16 v[18:33], v[234:237], v[238:241], v[18:33]
	v_cmp_ne_u64_e32 vcc, 0, v[230:231]
	v_lshl_add_u64 v[234:235], v[170:171], 0, s[54:55]
	s_mov_b64 s[20:21], 0x1fc0
	v_cndmask_b32_e32 v233, -1, v230, vcc
	v_cmp_ne_u64_e32 vcc, 0, v[234:235]
	v_lshl_add_u64 v[170:171], v[170:171], 0, s[20:21]
	ds_read_b64_tr_b16 v[230:231], v232
	ds_read_b64_tr_b16 v[232:233], v233
	v_cndmask_b32_e32 v234, -1, v234, vcc
	v_cmp_ne_u64_e32 vcc, 0, v[170:171]
	s_waitcnt lgkmcnt(0)
	v_mfma_f32_32x32x16_bf16 v[2:17], v[230:233], v[242:245], v[2:17]
	v_cndmask_b32_e32 v170, -1, v170, vcc
	ds_read_b64_tr_b16 v[234:235], v234
	ds_read_b64_tr_b16 v[236:237], v170
	s_andn2_b64 vcc, exec, s[12:13]
	s_waitcnt lgkmcnt(0)
	v_mfma_f32_32x32x16_bf16 v[18:33], v[234:237], v[242:245], v[18:33]
	s_waitcnt lgkmcnt(0)
	s_cbranch_vccnz .LBB0_2329
	v_lshl_add_u64 v[138:139], v[182:183], 0, s[10:11]
	v_add_co_u32_e32 v94, vcc, 0xe078000, v138
	s_nop 1
	v_addc_co_u32_e32 v95, vcc, 0, v139, vcc
	v_add_co_u32_e32 v106, vcc, 0xe087000, v138
	s_nop 1
	v_addc_co_u32_e32 v107, vcc, 0, v139, vcc
	v_add_co_u32_e32 v122, vcc, 0xe096000, v138
	global_load_dwordx4 v[94:97], v[94:95], off offset:2944
	s_nop 0
	global_load_dwordx4 v[106:109], v[106:107], off offset:2944
	v_addc_co_u32_e32 v123, vcc, 0, v139, vcc
	v_add_co_u32_e32 v126, vcc, 0xe0a5000, v138
	s_nop 1
	v_addc_co_u32_e32 v127, vcc, 0, v139, vcc
	v_add_co_u32_e32 v130, vcc, 0xe0b4000, v138
	global_load_dwordx4 v[122:125], v[122:123], off offset:2944
	s_nop 0
	global_load_dwordx4 v[126:129], v[126:127], off offset:2944
	v_addc_co_u32_e32 v131, vcc, 0, v139, vcc
	v_add_co_u32_e32 v134, vcc, 0xe0c3000, v138
	s_nop 1
	v_addc_co_u32_e32 v135, vcc, 0, v139, vcc
	v_add_co_u32_e32 v140, vcc, 0xe0d2000, v138
	global_load_dwordx4 v[130:133], v[130:131], off offset:2944
	s_nop 0
	global_load_dwordx4 v[134:137], v[134:135], off offset:2944
	v_addc_co_u32_e32 v141, vcc, 0, v139, vcc
	v_add_co_u32_e32 v142, vcc, 0xe0e1000, v138
	s_nop 1
	v_addc_co_u32_e32 v143, vcc, 0, v139, vcc
	global_load_dwordx4 v[138:141], v[140:141], off offset:2944
	s_nop 0
	global_load_dwordx4 v[142:145], v[142:143], off offset:2944

.LBB0_2344:
	v_max3_f32 v99, v50, v51, v52
	v_max3_f32 v100, v34, v35, v36
	v_and_b32_e32 v101, 64, v217
	v_max3_f32 v99, v99, v53, v54
	v_max3_f32 v100, v100, v37, v38
	v_add_u32_e32 v101, 64, v101
	v_max3_f32 v99, v99, v55, v56
	v_max3_f32 v100, v100, v39, v40
	s_nop 0
	v_max3_f32 v99, v99, v57, v58
	v_max3_f32 v100, v100, v41, v42
	s_nop 0
	v_max3_f32 v99, v99, v59, v60
	v_max3_f32 v100, v100, v43, v44
	s_nop 0
	v_max3_f32 v99, v99, v61, v62
	v_max3_f32 v100, v100, v45, v46
	s_nop 0
	v_max3_f32 v99, v99, v63, v64
	v_max3_f32 v100, v100, v47, v48
	s_nop 0
	v_max3_f32 v99, v99, v100, v65
	v_xor_b32_e32 v100, 32, v217
	v_cmp_lt_i32_e32 vcc, v100, v101
	v_max_f32_e32 v99, v99, v49
	s_nop 1
	v_cndmask_b32_e32 v100, v217, v100, vcc
	v_lshlrev_b32_e32 v100, 2, v100
	ds_bpermute_b32 v100, v100, v99
	s_waitcnt lgkmcnt(0)
	v_max_f32_e32 v99, v99, v100
	s_nop 0
	v_max_f32_e32 v109, v98, v99
	s_nop 0
	v_cmp_neq_f32_e32 vcc, s39, v109
	s_nop 1
	v_cndmask_b32_e32 v99, 0, v109, vcc
	v_sub_f32_e32 v34, v34, v99
	v_sub_f32_e32 v50, v50, v99
	v_exp_f32_e32 v131, v34
	v_sub_f32_e32 v34, v51, v99
	v_exp_f32_e32 v130, v50
	v_exp_f32_e32 v50, v34
	v_sub_f32_e32 v34, v35, v99
	v_exp_f32_e32 v148, v34
	v_sub_f32_e32 v34, v52, v99
	v_exp_f32_e32 v35, v34
	v_sub_f32_e32 v34, v36, v99
	v_exp_f32_e32 v132, v34
	v_sub_f32_e32 v34, v53, v99
	v_sub_f32_e32 v101, v98, v99
	v_exp_f32_e32 v98, v34
	v_sub_f32_e32 v34, v37, v99
	v_exp_f32_e32 v100, v34
	v_sub_f32_e32 v34, v54, v99
	v_exp_f32_e32 v37, v34
	v_sub_f32_e32 v34, v38, v99
	v_sub_f32_e32 v38, v56, v99
	v_sub_f32_e32 v36, v39, v99
	v_exp_f32_e32 v39, v38
	v_sub_f32_e32 v38, v40, v99
	v_exp_f32_e32 v53, v34
	v_sub_f32_e32 v34, v55, v99
	v_exp_f32_e32 v55, v38
	v_sub_f32_e32 v38, v57, v99
	v_exp_f32_e32 v40, v38
	v_sub_f32_e32 v38, v41, v99
	v_exp_f32_e32 v54, v38
	v_sub_f32_e32 v38, v58, v99
	v_exp_f32_e32 v57, v38
	v_sub_f32_e32 v38, v42, v99
	v_exp_f32_e32 v133, v38
	v_sub_f32_e32 v38, v59, v99
	v_exp_f32_e32 v52, v38
	v_sub_f32_e32 v38, v43, v99
	v_exp_f32_e32 v56, v38
	v_sub_f32_e32 v38, v60, v99
	v_exp_f32_e32 v43, v38
	v_sub_f32_e32 v38, v44, v99
	v_sub_f32_e32 v41, v47, v99
	v_exp_f32_e32 v59, v38
	v_sub_f32_e32 v38, v61, v99
	v_exp_f32_e32 v42, v41
	v_sub_f32_e32 v41, v64, v99
	v_exp_f32_e32 v58, v38
	v_sub_f32_e32 v38, v45, v99
	v_exp_f32_e32 v47, v41
	v_sub_f32_e32 v41, v48, v99
	v_exp_f32_e32 v60, v38
	v_sub_f32_e32 v38, v62, v99
	v_exp_f32_e32 v134, v41
	v_sub_f32_e32 v41, v65, v99
	v_exp_f32_e32 v45, v38
	v_sub_f32_e32 v38, v46, v99
	v_exp_f32_e32 v46, v41
	v_sub_f32_e32 v41, v49, v99
	v_exp_f32_e32 v48, v41
	v_lshlrev_b32_e32 v41, 1, v154
	v_add3_u32 v41, s9, v105, v41
	v_exp_f32_e32 v61, v38
	v_sub_f32_e32 v38, v63, v99
	v_add_u32_e32 v49, 0x2000, v41
	v_exp_f32_e32 v34, v34
	v_exp_f32_e32 v36, v36
	v_exp_f32_e32 v38, v38
	v_cvt_pk_bf16_f32 v62, v130, v50
	v_cvt_pk_bf16_f32 v63, v35, v98
	v_cvt_pk_bf16_f32 v64, v37, v34
	v_cvt_pk_bf16_f32 v65, v39, v40
	v_cvt_pk_bf16_f32 v110, v57, v52
	v_cvt_pk_bf16_f32 v111, v43, v58
	v_cvt_pk_bf16_f32 v112, v45, v38
	v_cvt_pk_bf16_f32 v113, v47, v46
	v_cvt_pk_bf16_f32 v114, v131, v148
	v_cvt_pk_bf16_f32 v115, v132, v100
	v_cvt_pk_bf16_f32 v116, v53, v36
	v_cvt_pk_bf16_f32 v117, v55, v54
	v_cvt_pk_bf16_f32 v118, v133, v56
	v_cvt_pk_bf16_f32 v119, v59, v60
	v_cvt_pk_bf16_f32 v120, v61, v42
	v_cvt_pk_bf16_f32 v121, v134, v48
	ds_read2_b64 v[122:125], v49 offset0:128 offset1:130
	v_add_u32_e32 v135, 0x3000, v41
	ds_read2_b64 v[126:129], v135 offset0:160 offset1:162
	v_exp_f32_e32 v44, v101
	v_add_f32_e32 v51, v130, v131
	v_add_f32_e32 v50, v50, v148
	v_add_f32_e32 v51, v51, v149
	v_add_f32_e32 v99, v35, v132
	v_mul_f32_e32 v32, v32, v44
	v_mul_f32_e32 v33, v33, v44
	v_mul_f32_e32 v30, v30, v44
	v_mul_f32_e32 v31, v31, v44
	v_mul_f32_e32 v28, v28, v44
	v_mul_f32_e32 v29, v29, v44
	v_mul_f32_e32 v26, v26, v44
	v_mul_f32_e32 v27, v27, v44
	v_mul_f32_e32 v24, v24, v44
	v_mul_f32_e32 v25, v25, v44
	v_mul_f32_e32 v22, v22, v44
	v_mul_f32_e32 v23, v23, v44
	v_mul_f32_e32 v20, v20, v44
	v_mul_f32_e32 v21, v21, v44
	v_mul_f32_e32 v18, v18, v44
	v_mul_f32_e32 v19, v19, v44
	v_mul_f32_e32 v16, v16, v44
	v_mul_f32_e32 v17, v17, v44
	v_mul_f32_e32 v14, v14, v44
	v_mul_f32_e32 v15, v15, v44
	s_waitcnt lgkmcnt(1)
	v_mfma_f32_32x32x16_bf16 v[18:33], v[122:125], v[62:65], v[18:33]
	v_mul_f32_e64 v12, v12, v44
	v_mul_f32_e64 v13, v13, v44
	v_mul_f32_e64 v10, v10, v44
	v_mul_f32_e64 v11, v11, v44
	v_mul_f32_e64 v8, v8, v44
	v_mul_f32_e64 v9, v9, v44
	v_mul_f32_e32 v6, v6, v44
	v_mul_f32_e32 v7, v7, v44
	v_mul_f32_e32 v4, v4, v44
	v_mul_f32_e32 v5, v5, v44
	v_mul_f32_e32 v2, v2, v44
	v_mul_f32_e32 v3, v3, v44
	v_add_f32_e32 v51, v50, v51
	v_add_f32_e32 v50, v50, v50
	v_mov_b32_e32 v101, v51
	s_waitcnt lgkmcnt(0)
	v_mfma_f32_32x32x16_bf16 v[2:17], v[126:129], v[62:65], v[2:17]
	ds_read2_b64 v[62:65], v49 offset0:132 offset1:134
	ds_read2_b64 v[122:125], v135 offset0:164 offset1:166
	v_add_f32_e64 v50, v98, v100
	v_add_f32_e64 v51, v99, v101
	ds_read2_b64 v[98:101], v135 offset0:168 offset1:170
	v_add_f32_e32 v51, v50, v51
	v_add_f32_e32 v50, v50, v50
	v_add_f32_e32 v35, v37, v53
	v_mov_b32_e32 v37, v51
	v_add_f32_e32 v34, v34, v36
	v_add_f32_e32 v35, v35, v37
	s_waitcnt lgkmcnt(2)
	v_mfma_f32_32x32x16_bf16 v[18:33], v[62:65], v[110:113], v[18:33]
	ds_read2_b64 v[62:65], v49 offset0:136 offset1:138
	v_add_f32_e32 v35, v34, v35
	v_add_f32_e32 v34, v34, v34
	v_add_f32_e32 v41, v39, v55
	v_mov_b32_e32 v55, v35
	v_add_f32_e32 v40, v40, v54
	v_add_f32_e32 v41, v41, v55
	v_add_f32_e32 v53, v57, v133
	v_add_f32_e32 v41, v40, v41
	v_add_f32_e32 v40, v40, v40
	s_waitcnt lgkmcnt(2)
	v_mfma_f32_32x32x16_bf16 v[2:17], v[122:125], v[110:113], v[2:17]
	ds_read2_b64 v[34:37], v49 offset0:140 offset1:142
	v_mov_b32_e32 v57, v41
	v_add_f32_e64 v40, v52, v56
	v_add_f32_e64 v41, v53, v57
	ds_read2_b64 v[50:53], v135 offset0:172 offset1:174
	v_add_f32_e32 v41, v40, v41
	v_add_f32_e32 v40, v40, v40
	v_add_f32_e32 v59, v43, v59
	v_add_f32_e32 v39, v45, v61
	s_waitcnt lgkmcnt(2)
	v_mfma_f32_32x32x16_bf16 v[18:33], v[62:65], v[114:117], v[18:33]
	v_mov_b32_e32 v61, v41
	v_add_f32_e64 v40, v58, v60
	v_add_f32_e64 v41, v59, v61
	v_add_f32_e32 v47, v47, v134
	v_mfma_f32_32x32x16_bf16 v[2:17], v[98:101], v[114:117], v[2:17]
	v_mov_b32_e32 v98, v109
	s_waitcnt lgkmcnt(1)
	v_mfma_f32_32x32x16_bf16 v[18:33], v[34:37], v[118:121], v[18:33]
	v_add_f32_e64 v34, v40, v40
	v_add_f32_e64 v35, v40, v41
	v_mov_b32_e32 v43, v35
	v_add_f32_e64 v34, v38, v42
	v_add_f32_e64 v35, v39, v43
	v_add_f32_e32 v35, v34, v35
	v_add_f32_e32 v34, v34, v34
	v_mov_b32_e32 v49, v35
	v_add_f32_e32 v34, v46, v48
	v_add_f32_e32 v35, v47, v49
	s_waitcnt lgkmcnt(0)
	v_mfma_f32_32x32x16_bf16 v[2:17], v[50:53], v[118:121], v[2:17]
	v_add_f32_e32 v34, v34, v35
	v_fmac_f32_e32 v34, v108, v44
	v_mov_b32_e32 v108, v34
	s_andn2_b64 vcc, exec, s[6:7]
	s_xor_b32 s8, s8, 1
	s_cbranch_vccnz .LBB0_2337

.LBB0_2346:
	v_and_b32_e32 v35, 64, v217
	v_xor_b32_e32 v34, 32, v217
	v_add_u32_e32 v35, 64, v35
	v_cmp_lt_i32_e32 vcc, v34, v35
	v_lshl_add_u32 v36, v223, 1, v223
	v_mov_b32_e32 v155, v149
	v_cndmask_b32_e32 v34, v217, v34, vcc
	v_lshlrev_b32_e32 v34, 2, v34
	ds_bpermute_b32 v34, v34, v108
	v_cmp_lt_i32_e32 vcc, -1, v221
	s_waitcnt lgkmcnt(0)
	v_add_f32_e32 v34, v108, v34
	s_and_saveexec_b64 s[6:7], vcc
	s_cbranch_execz .LBB0_2351
	v_mov_b64_e32 v[38:39], s[86:87]
	s_movk_i32 s0, 0x110
	v_mad_i64_i32 v[38:39], s[0:1], v36, s0, v[38:39]
	global_load_dwordx2 v[70:71], v[38:39], off offset:256
	v_lshl_add_u64 v[66:67], v[154:155], 2, v[38:39]
	global_load_dwordx4 v[38:41], v[66:67], off offset:128
	global_load_dwordx4 v[42:45], v[66:67], off offset:32
	global_load_dwordx4 v[46:49], v[66:67], off offset:160
	global_load_dwordx4 v[50:53], v[66:67], off offset:64
	global_load_dwordx4 v[54:57], v[66:67], off offset:192
	global_load_dwordx4 v[58:61], v[66:67], off offset:96
	global_load_dwordx4 v[62:65], v[66:67], off offset:224
	s_nop 0
	global_load_dwordx4 v[66:69], v[66:67], off
	s_waitcnt vmcnt(8)
	v_max_f32_e32 v37, v98, v70
	s_nop 0
	v_sub_f32_e32 v35, v98, v37
	v_mov_b32_e32 v98, v37
	v_sub_f32_e32 v72, v70, v37
	v_exp_f32_e32 v70, v35
	v_exp_f32_e32 v72, v72
	v_mov_b32_e32 v35, v71
	v_mul_f32_e32 v18, v18, v70
	v_mul_f32_e32 v19, v19, v70
	v_mul_f32_e32 v20, v20, v70
	v_mul_f32_e32 v21, v21, v70
	s_waitcnt vmcnt(6)
	v_mul_f32_e32 v42, v72, v42
	v_mul_f32_e32 v43, v72, v43
	s_waitcnt vmcnt(2)
	v_mul_f32_e32 v74, v72, v60
	s_waitcnt vmcnt(1)
	v_mul_f32_e32 v76, v72, v64
	v_mov_b32_e32 v60, v33
	v_mov_b32_e32 v71, v72
	v_mov_b32_e32 v64, v17
	v_mul_f32_e32 v60, v60, v70
	v_mul_f32_e32 v61, v61, v71
	v_fma_f32 v22, v22, v70, v42
	v_fma_f32 v23, v23, v70, v43
	v_mul_f32_e32 v42, v64, v70
	v_mul_f32_e32 v43, v65, v71
	v_mul_f32_e32 v38, v72, v38
	v_mul_f32_e32 v39, v72, v39
	v_mul_f32_e32 v40, v72, v40
	v_mul_f32_e32 v41, v72, v41
	v_mul_f32_e32 v46, v72, v46
	v_mul_f32_e32 v47, v72, v47
	v_mul_f32_e32 v44, v72, v44
	v_mul_f32_e32 v45, v72, v45
	v_mul_f32_e32 v48, v72, v48
	v_mul_f32_e32 v49, v72, v49
	v_mul_f32_e32 v50, v72, v50
	v_mul_f32_e32 v51, v72, v51
	v_mul_f32_e32 v54, v72, v54
	v_mul_f32_e32 v55, v72, v55
	v_mul_f32_e32 v52, v72, v52
	v_mul_f32_e32 v53, v72, v53
	v_mul_f32_e32 v56, v72, v56
	v_mul_f32_e32 v57, v72, v57
	v_mul_f32_e32 v58, v72, v58
	v_mul_f32_e32 v59, v72, v59
	v_mul_f32_e32 v62, v72, v62
	v_mul_f32_e32 v63, v72, v63
	v_mul_f32_e32 v32, v32, v70
	v_mul_f32_e32 v16, v16, v70
	v_mul_f32_e32 v34, v34, v70
	v_mul_f32_e32 v35, v35, v71
	v_mov_b32_e32 v33, v60
	v_mov_b32_e32 v75, v61
	v_mov_b32_e32 v17, v42
	v_mov_b32_e32 v77, v43
	s_waitcnt vmcnt(0)
	v_fma_f32 v18, v72, v66, v18
	v_fma_f32 v19, v72, v67, v19
	v_fma_f32 v20, v72, v68, v20
	v_fma_f32 v21, v72, v69, v21
	v_fma_f32 v24, v24, v70, v44
	v_fma_f32 v25, v25, v70, v45
	v_fma_f32 v26, v26, v70, v50
	v_fma_f32 v27, v27, v70, v51
	v_fma_f32 v28, v28, v70, v52
	v_fma_f32 v29, v29, v70, v53
	v_fma_f32 v30, v30, v70, v58
	v_fma_f32 v31, v31, v70, v59
	v_fma_f32 v2, v2, v70, v38
	v_fma_f32 v3, v3, v70, v39
	v_fma_f32 v4, v4, v70, v40
	v_fma_f32 v5, v5, v70, v41
	v_fma_f32 v6, v6, v70, v46
	v_fma_f32 v7, v7, v70, v47
	v_fma_f32 v8, v8, v70, v48
	v_fma_f32 v9, v9, v70, v49
	v_fma_f32 v10, v10, v70, v54
	v_fma_f32 v11, v11, v70, v55
	v_fma_f32 v12, v12, v70, v56
	v_fma_f32 v13, v13, v70, v57
	v_fma_f32 v14, v14, v70, v62
	v_fma_f32 v15, v15, v70, v63
	v_add_f32_e32 v34, v34, v35
	v_add_f32_e32 v32, v32, v74
	v_add_f32_e32 v33, v33, v75
	v_add_f32_e32 v16, v16, v76
	v_add_f32_e32 v17, v17, v77
	s_or_b64 exec, exec, s[6:7]
	v_cmp_lt_i32_e32 vcc, -1, v220
	s_and_saveexec_b64 s[6:7], vcc
	s_cbranch_execnz .LBB0_2352

.LBB0_2349:
	v_add_u32_e32 v35, 2, v36
	v_mov_b64_e32 v[36:37], s[86:87]
	s_movk_i32 s0, 0x110
	v_mad_i64_i32 v[36:37], s[0:1], v35, s0, v[36:37]
	global_load_dwordx2 v[68:69], v[36:37], off offset:256
	v_lshl_add_u64 v[64:65], v[154:155], 2, v[36:37]
	global_load_dwordx4 v[36:39], v[64:65], off offset:128
	global_load_dwordx4 v[40:43], v[64:65], off offset:32
	global_load_dwordx4 v[44:47], v[64:65], off offset:160
	global_load_dwordx4 v[48:51], v[64:65], off offset:64
	global_load_dwordx4 v[52:55], v[64:65], off offset:192
	global_load_dwordx4 v[56:59], v[64:65], off offset:96
	global_load_dwordx4 v[60:63], v[64:65], off offset:224
	s_nop 0
	global_load_dwordx4 v[64:67], v[64:65], off
	s_waitcnt vmcnt(8)
	v_max_f32_e32 v35, v98, v68
	s_nop 0
	v_sub_f32_e32 v70, v98, v35
	v_sub_f32_e32 v35, v68, v35
	v_exp_f32_e32 v68, v70
	v_exp_f32_e32 v70, v35
	v_mov_b32_e32 v35, v69
	v_mul_f32_e32 v18, v18, v68
	v_mul_f32_e32 v19, v19, v68
	v_mul_f32_e32 v20, v20, v68
	v_mul_f32_e32 v21, v21, v68
	s_waitcnt vmcnt(6)
	v_mul_f32_e32 v40, v70, v40
	v_mul_f32_e32 v41, v70, v41
	s_waitcnt vmcnt(2)
	v_mul_f32_e32 v72, v70, v58
	s_waitcnt vmcnt(1)
	v_mul_f32_e32 v74, v70, v62
	v_mov_b32_e32 v58, v33
	v_mov_b32_e32 v69, v70
	v_mov_b32_e32 v62, v17
	v_mul_f32_e32 v58, v58, v68
	v_mul_f32_e32 v59, v59, v69
	v_fma_f32 v22, v22, v68, v40
	v_fma_f32 v23, v23, v68, v41
	v_mul_f32_e32 v40, v62, v68
	v_mul_f32_e32 v41, v63, v69
	v_mul_f32_e32 v36, v70, v36
	v_mul_f32_e32 v37, v70, v37
	v_mul_f32_e32 v38, v70, v38
	v_mul_f32_e32 v39, v70, v39
	v_mul_f32_e32 v44, v70, v44
	v_mul_f32_e32 v45, v70, v45
	v_mul_f32_e32 v42, v70, v42
	v_mul_f32_e32 v43, v70, v43
	v_mul_f32_e32 v46, v70, v46
	v_mul_f32_e32 v47, v70, v47
	v_mul_f32_e32 v48, v70, v48
	v_mul_f32_e32 v49, v70, v49
	v_mul_f32_e32 v52, v70, v52
	v_mul_f32_e32 v53, v70, v53
	v_mul_f32_e32 v50, v70, v50
	v_mul_f32_e32 v51, v70, v51
	v_mul_f32_e32 v54, v70, v54
	v_mul_f32_e32 v55, v70, v55
	v_mul_f32_e32 v56, v70, v56
	v_mul_f32_e32 v57, v70, v57
	v_mul_f32_e32 v60, v70, v60
	v_mul_f32_e32 v61, v70, v61
	v_mul_f32_e32 v32, v32, v68
	v_mul_f32_e32 v16, v16, v68
	v_mul_f32_e32 v34, v34, v68
	v_mul_f32_e32 v35, v35, v69
	v_mov_b32_e32 v33, v58
	v_mov_b32_e32 v73, v59
	v_mov_b32_e32 v17, v40
	v_mov_b32_e32 v75, v41
	s_waitcnt vmcnt(0)
	v_fma_f32 v18, v70, v64, v18
	v_fma_f32 v19, v70, v65, v19
	v_fma_f32 v20, v70, v66, v20
	v_fma_f32 v21, v70, v67, v21
	v_fma_f32 v24, v24, v68, v42
	v_fma_f32 v25, v25, v68, v43
	v_fma_f32 v26, v26, v68, v48
	v_fma_f32 v27, v27, v68, v49
	v_fma_f32 v28, v28, v68, v50
	v_fma_f32 v29, v29, v68, v51
	v_fma_f32 v30, v30, v68, v56
	v_fma_f32 v31, v31, v68, v57
	v_fma_f32 v2, v2, v68, v36
	v_fma_f32 v3, v3, v68, v37
	v_fma_f32 v4, v4, v68, v38
	v_fma_f32 v5, v5, v68, v39
	v_fma_f32 v6, v6, v68, v44
	v_fma_f32 v7, v7, v68, v45
	v_fma_f32 v8, v8, v68, v46
	v_fma_f32 v9, v9, v68, v47
	v_fma_f32 v10, v10, v68, v52
	v_fma_f32 v11, v11, v68, v53
	v_fma_f32 v12, v12, v68, v54
	v_fma_f32 v13, v13, v68, v55
	v_fma_f32 v14, v14, v68, v60
	v_fma_f32 v15, v15, v68, v61
	v_add_f32_e32 v32, v32, v72
	v_add_f32_e32 v33, v33, v73
	v_add_f32_e32 v16, v16, v74
	v_add_f32_e32 v17, v17, v75
	v_add_f32_e32 v34, v34, v35

.LBB0_4549:
	s_mul_i32 s4, s22, 0x4700
	s_addk_i32 s4, 0x100
	v_add3_u32 v105, s4, v124, v126
	ds_read_b128 v[34:37], v105
	ds_read_b128 v[106:109], v105 offset:32
	s_add_i32 s5, s20, 63
	s_cmp_le_i32 s5, s18
	s_waitcnt lgkmcnt(1)
	v_mfma_f32_32x32x16_bf16 v[50:65], v[34:37], v[66:69], 0
	ds_read_b128 v[34:37], v105 offset:4608
	ds_read_b128 v[110:113], v105 offset:4640
	s_waitcnt lgkmcnt(1)
	v_mfma_f32_32x32x16_bf16 v[34:49], v[34:37], v[66:69], 0
	v_mfma_f32_32x32x16_bf16 v[50:65], v[106:109], v[70:73], v[50:65]
	s_waitcnt lgkmcnt(0)
	v_mfma_f32_32x32x16_bf16 v[34:49], v[110:113], v[70:73], v[34:49]
	ds_read_b128 v[106:109], v105 offset:64
	ds_read_b128 v[110:113], v105 offset:96
	s_waitcnt lgkmcnt(1)
	v_mfma_f32_32x32x16_bf16 v[50:65], v[106:109], v[74:77], v[50:65]
	ds_read_b128 v[106:109], v105 offset:4672
	ds_read_b128 v[128:131], v105 offset:4704
	v_lshl_add_u32 v105, v98, 2, s4
	ds_read_b128 v[132:135], v105 offset:17920
	ds_read_b128 v[136:139], v105 offset:17952
	s_waitcnt lgkmcnt(3)
	v_mfma_f32_32x32x16_bf16 v[34:49], v[106:109], v[74:77], v[34:49]
	v_mfma_f32_32x32x16_bf16 v[50:65], v[110:113], v[78:81], v[50:65]
	ds_read_b128 v[140:143], v105 offset:17984
	ds_read_b128 v[112:115], v105 offset:18016
	ds_read_b128 v[150:153], v105 offset:18048
	ds_read_b128 v[154:157], v105 offset:18080
	ds_read_b128 v[158:161], v105 offset:18112
	ds_read_b128 v[162:165], v105 offset:18144
	s_waitcnt lgkmcnt(4)
	s_nop 4
	v_add_f32_e32 v110, v64, v114
	v_add_f32_e32 v111, v65, v115
	v_mfma_f32_32x32x16_bf16 v[34:49], v[128:131], v[78:81], v[34:49]
	v_add_f32_e64 v112, v62, v112
	v_add_f32_e64 v113, v63, v113
	v_add_f32_e64 v114, v60, v142
	v_add_f32_e64 v115, v61, v143
	v_add_f32_e64 v58, v58, v140
	v_add_f32_e64 v59, v59, v141
	v_add_f32_e32 v60, v56, v138
	v_add_f32_e32 v61, v57, v139
	v_add_f32_e32 v54, v54, v136
	v_add_f32_e32 v55, v55, v137
	v_add_f32_e32 v52, v52, v134
	v_add_f32_e32 v53, v53, v135
	v_add_f32_e32 v50, v50, v132
	v_add_f32_e32 v51, v51, v133
	s_waitcnt lgkmcnt(0)
	s_nop 0
	v_add_f32_e32 v48, v48, v164
	v_add_f32_e32 v49, v49, v165
	v_add_f32_e32 v116, v46, v162
	v_add_f32_e32 v117, v47, v163
	v_add_f32_e32 v44, v44, v160
	v_add_f32_e32 v45, v45, v161
	v_add_f32_e32 v42, v42, v158
	v_add_f32_e32 v43, v43, v159
	v_add_f32_e32 v40, v40, v156
	v_add_f32_e32 v41, v41, v157
	v_add_f32_e32 v38, v38, v154
	v_add_f32_e32 v39, v39, v155
	v_add_f32_e32 v36, v36, v152
	v_add_f32_e32 v37, v37, v153
	v_add_f32_e32 v34, v34, v150
	v_add_f32_e32 v35, v35, v151
	s_cbranch_scc1 .LBB0_4551
	v_add_u32_e32 v46, s20, v98
	v_add_u32_e32 v47, 32, v46
	v_cmp_le_i32_e32 vcc, v47, v96
	v_add_u32_e32 v47, 33, v46
	s_nop 0
	v_cndmask_b32_e32 v34, v216, v34, vcc
	v_cmp_lt_i32_e32 vcc, v46, v96
	s_nop 1
	v_cndmask_b32_e32 v51, v216, v51, vcc
	v_cmp_le_i32_e32 vcc, v46, v96
	s_nop 1
	v_cndmask_b32_e32 v50, v216, v50, vcc
	v_cmp_le_i32_e32 vcc, v47, v96
	v_add_u32_e32 v47, 2, v46
	s_nop 0
	v_cndmask_b32_e32 v35, v216, v35, vcc
	v_cmp_le_i32_e32 vcc, v47, v96
	v_add_u32_e32 v47, 34, v46
	s_nop 0
	v_cndmask_b32_e32 v52, v216, v52, vcc
	v_cmp_le_i32_e32 vcc, v47, v96
	v_add_u32_e32 v47, 3, v46
	s_nop 0
	v_cndmask_b32_e32 v36, v216, v36, vcc
	v_cmp_le_i32_e32 vcc, v47, v96
	v_add_u32_e32 v47, 35, v46
	s_nop 0
	v_cndmask_b32_e32 v53, v216, v53, vcc
	v_cmp_le_i32_e32 vcc, v47, v96
	v_add_u32_e32 v47, 8, v46
	s_nop 0
	v_cndmask_b32_e32 v37, v216, v37, vcc
	v_cmp_le_i32_e32 vcc, v47, v96
	v_add_u32_e32 v47, 40, v46
	s_nop 0
	v_cndmask_b32_e32 v54, v216, v54, vcc
	v_cmp_le_i32_e32 vcc, v47, v96
	v_add_u32_e32 v47, 9, v46
	s_nop 0
	v_cndmask_b32_e32 v38, v216, v38, vcc
	v_cmp_le_i32_e32 vcc, v47, v96
	v_add_u32_e32 v47, 41, v46
	s_nop 0
	v_cndmask_b32_e32 v55, v216, v55, vcc
	v_cmp_le_i32_e32 vcc, v47, v96
	v_add_u32_e32 v47, 10, v46
	s_nop 0
	v_cndmask_b32_e32 v39, v216, v39, vcc
	v_cmp_le_i32_e32 vcc, v47, v96
	v_add_u32_e32 v47, 42, v46
	s_nop 0
	v_cndmask_b32_e32 v60, v216, v60, vcc
	v_cmp_le_i32_e32 vcc, v47, v96
	v_add_u32_e32 v47, 11, v46
	s_nop 0
	v_cndmask_b32_e32 v40, v216, v40, vcc
	v_cmp_le_i32_e32 vcc, v47, v96
	v_add_u32_e32 v47, 43, v46
	s_nop 0
	v_cndmask_b32_e32 v61, v216, v61, vcc
	v_cmp_le_i32_e32 vcc, v47, v96
	v_add_u32_e32 v47, 16, v46
	s_nop 0
	v_cndmask_b32_e32 v41, v216, v41, vcc
	v_cmp_le_i32_e32 vcc, v47, v96
	v_add_u32_e32 v47, 48, v46
	s_nop 0
	v_cndmask_b32_e32 v58, v216, v58, vcc
	v_cmp_le_i32_e32 vcc, v47, v96
	v_add_u32_e32 v47, 17, v46
	s_nop 0
	v_cndmask_b32_e32 v42, v216, v42, vcc
	v_cmp_le_i32_e32 vcc, v47, v96
	v_add_u32_e32 v47, 49, v46
	s_nop 0
	v_cndmask_b32_e32 v59, v216, v59, vcc
	v_cmp_le_i32_e32 vcc, v47, v96
	v_add_u32_e32 v47, 18, v46
	s_nop 0
	v_cndmask_b32_e32 v43, v216, v43, vcc
	v_cmp_le_i32_e32 vcc, v47, v96
	v_add_u32_e32 v47, 50, v46
	s_nop 0
	v_cndmask_b32_e32 v114, v216, v114, vcc
	v_cmp_le_i32_e32 vcc, v47, v96
	v_add_u32_e32 v47, 19, v46
	s_nop 0
	v_cndmask_b32_e32 v44, v216, v44, vcc
	v_cmp_le_i32_e32 vcc, v47, v96
	v_add_u32_e32 v47, 51, v46
	s_nop 0
	v_cndmask_b32_e32 v115, v216, v115, vcc
	v_cmp_le_i32_e32 vcc, v47, v96
	v_add_u32_e32 v47, 24, v46
	s_nop 0
	v_cndmask_b32_e32 v45, v216, v45, vcc
	v_cmp_le_i32_e32 vcc, v47, v96
	v_add_u32_e32 v47, 56, v46
	s_nop 0
	v_cndmask_b32_e32 v112, v216, v112, vcc
	v_cmp_le_i32_e32 vcc, v47, v96
	v_add_u32_e32 v47, 25, v46
	s_nop 0
	v_cndmask_b32_e32 v116, v216, v116, vcc
	v_cmp_le_i32_e32 vcc, v47, v96
	v_add_u32_e32 v47, 57, v46
	s_nop 0
	v_cndmask_b32_e32 v113, v216, v113, vcc
	v_cmp_le_i32_e32 vcc, v47, v96
	v_add_u32_e32 v47, 26, v46
	s_nop 0
	v_cndmask_b32_e32 v117, v216, v117, vcc
	v_cmp_le_i32_e32 vcc, v47, v96
	v_add_u32_e32 v47, 58, v46
	s_nop 0
	v_cndmask_b32_e32 v110, v216, v110, vcc
	v_cmp_le_i32_e32 vcc, v47, v96
	v_add_u32_e32 v47, 27, v46
	v_add_u32_e32 v46, 59, v46
	v_cndmask_b32_e32 v48, v216, v48, vcc
	v_cmp_le_i32_e32 vcc, v47, v96
	s_nop 1
	v_cndmask_b32_e32 v111, v216, v111, vcc
	v_cmp_le_i32_e32 vcc, v46, v96
	s_nop 1
	v_cndmask_b32_e32 v49, v216, v49, vcc
.LBB0_4551:
	v_max3_f32 v46, v50, v51, v52
	v_max3_f32 v47, v34, v35, v36
	s_nop 0
	v_max3_f32 v46, v46, v53, v54
	v_max3_f32 v47, v47, v37, v38
	s_nop 0
	v_max3_f32 v46, v46, v55, v60
	v_max3_f32 v47, v47, v39, v40
	s_nop 0
	v_max3_f32 v46, v46, v61, v58
	v_max3_f32 v47, v47, v41, v42
	s_nop 0
	v_max3_f32 v46, v46, v59, v114
	v_max3_f32 v47, v47, v43, v44
	s_nop 0
	v_max3_f32 v46, v46, v115, v112
	v_max3_f32 v47, v47, v45, v116
	s_nop 0
	v_max3_f32 v46, v46, v113, v110
	v_max3_f32 v47, v47, v117, v48
	s_nop 0
	v_max3_f32 v46, v46, v47, v111
	s_nop 0
	v_max_f32_e32 v46, v46, v49
	ds_bpermute_b32 v47, v97, v46
	s_waitcnt lgkmcnt(0)
	v_max_f32_e32 v46, v46, v47
	s_nop 0
	v_max_f32_e32 v127, v104, v46
	s_nop 0
	v_cmp_neq_f32_e32 vcc, s39, v127
	s_nop 1
	v_cndmask_b32_e32 v47, 0, v127, vcc
	v_sub_f32_e32 v34, v34, v47
	v_exp_f32_e32 v65, v34
	v_sub_f32_e32 v34, v51, v47
	v_exp_f32_e32 v64, v34
	v_sub_f32_e32 v34, v35, v47
	v_sub_f32_e32 v57, v104, v47
	v_exp_f32_e32 v104, v34
	v_sub_f32_e32 v34, v52, v47
	v_exp_f32_e32 v51, v34
	v_sub_f32_e32 v34, v36, v47
	v_exp_f32_e32 v107, v34
	v_sub_f32_e32 v34, v53, v47
	v_exp_f32_e32 v106, v34
	v_sub_f32_e32 v34, v37, v47
	v_exp_f32_e32 v108, v34
	v_sub_f32_e32 v34, v54, v47
	v_exp_f32_e32 v53, v34
	v_sub_f32_e32 v34, v38, v47
	v_exp_f32_e32 v140, v34
	v_sub_f32_e32 v34, v55, v47
	v_exp_f32_e32 v52, v34
	v_sub_f32_e32 v34, v39, v47
	v_exp_f32_e32 v56, v34
	v_sub_f32_e32 v34, v60, v47
	v_exp_f32_e32 v39, v34
	v_sub_f32_e32 v34, v40, v47
	v_exp_f32_e32 v55, v34
	v_sub_f32_e32 v34, v61, v47
	v_exp_f32_e32 v60, v34
	v_sub_f32_e32 v34, v41, v47
	v_exp_f32_e32 v62, v34
	v_sub_f32_e32 v34, v58, v47
	v_exp_f32_e32 v41, v34
	v_sub_f32_e32 v34, v42, v47
	v_sub_f32_e32 v46, v50, v47
	v_exp_f32_e32 v61, v34
	v_sub_f32_e32 v34, v59, v47
	v_exp_f32_e32 v63, v46
	v_exp_f32_e32 v46, v34
	v_sub_f32_e32 v34, v43, v47
	v_exp_f32_e32 v50, v34
	v_sub_f32_e32 v34, v114, v47
	v_exp_f32_e32 v43, v34
	v_sub_f32_e32 v34, v44, v47
	v_exp_f32_e32 v59, v34
	v_sub_f32_e32 v34, v115, v47
	v_exp_f32_e32 v54, v34
	v_sub_f32_e32 v34, v45, v47
	v_exp_f32_e32 v58, v34
	v_sub_f32_e32 v34, v112, v47
	v_exp_f32_e32 v45, v34
	v_sub_f32_e32 v34, v116, v47
	v_exp_f32_e32 v141, v34
	v_sub_f32_e32 v34, v113, v47
	v_exp_f32_e32 v40, v34
	v_sub_f32_e32 v34, v117, v47
	v_exp_f32_e32 v42, v34
	v_sub_f32_e32 v34, v110, v47
	v_exp_f32_e32 v142, v34
	v_sub_f32_e32 v34, v48, v47
	v_exp_f32_e32 v143, v34
	v_sub_f32_e32 v34, v111, v47
	v_exp_f32_e32 v44, v34
	v_sub_f32_e32 v34, v49, v47
	v_lshlrev_b32_e32 v47, 1, v98
	v_add3_u32 v47, s4, v125, v47
	v_add_u32_e32 v144, 0x2000, v47
	v_add_u32_e32 v145, 0x3000, v47
	v_exp_f32_e32 v48, v34
	v_cvt_pk_bf16_f32 v110, v63, v64
	v_cvt_pk_bf16_f32 v111, v51, v106
	v_cvt_pk_bf16_f32 v112, v53, v52
	v_cvt_pk_bf16_f32 v113, v39, v60
	v_cvt_pk_bf16_f32 v114, v41, v46
	v_cvt_pk_bf16_f32 v115, v43, v54
	v_cvt_pk_bf16_f32 v116, v45, v40
	v_cvt_pk_bf16_f32 v117, v142, v44
	v_cvt_pk_bf16_f32 v128, v65, v104
	v_cvt_pk_bf16_f32 v129, v107, v108
	v_cvt_pk_bf16_f32 v130, v140, v56
	v_cvt_pk_bf16_f32 v131, v55, v62
	v_cvt_pk_bf16_f32 v34, v61, v50
	v_cvt_pk_bf16_f32 v35, v59, v58
	v_cvt_pk_bf16_f32 v36, v141, v42
	v_cvt_pk_bf16_f32 v37, v143, v48
	ds_read2_b64 v[132:135], v144 offset0:128 offset1:130
	ds_read2_b64 v[136:139], v145 offset0:160 offset1:162
	v_exp_f32_e32 v38, v57
	v_add_f32_e32 v105, v65, v63
	v_mov_b32_e32 v65, v149
	v_add_f32_e32 v64, v104, v64
	v_add_f32_e32 v65, v105, v65
	v_mul_f32_e32 v16, v16, v38
	v_mul_f32_e32 v17, v17, v38
	v_mul_f32_e32 v14, v14, v38
	v_mul_f32_e32 v15, v15, v38
	v_mul_f32_e32 v12, v12, v38
	v_mul_f32_e32 v13, v13, v38
	v_mul_f32_e32 v10, v10, v38
	v_mul_f32_e32 v11, v11, v38
	v_mul_f32_e32 v8, v8, v38
	v_mul_f32_e32 v9, v9, v38
	v_mul_f32_e32 v6, v6, v38
	v_mul_f32_e32 v7, v7, v38
	v_mul_f32_e32 v4, v4, v38
	v_mul_f32_e32 v5, v5, v38
	v_mul_f32_e32 v2, v2, v38
	v_mul_f32_e32 v3, v3, v38
	v_mul_f32_e32 v32, v32, v38
	v_mul_f32_e32 v33, v33, v38
	v_mul_f32_e32 v30, v30, v38
	v_mul_f32_e32 v31, v31, v38
	v_mul_f32_e32 v28, v28, v38
	v_mul_f32_e32 v29, v29, v38
	v_mul_f32_e32 v26, v26, v38
	v_mul_f32_e32 v27, v27, v38
	v_mul_f32_e32 v24, v24, v38
	v_mul_f32_e32 v25, v25, v38
	v_mul_f32_e32 v22, v22, v38
	v_mul_f32_e32 v23, v23, v38
	v_mul_f32_e32 v20, v20, v38
	v_mul_f32_e32 v21, v21, v38
	v_mul_f32_e32 v18, v18, v38
	v_mul_f32_e32 v19, v19, v38
	s_waitcnt lgkmcnt(1)
	v_mfma_f32_32x32x16_bf16 v[2:17], v[132:135], v[110:113], v[2:17]
	ds_read2_b64 v[132:135], v145 offset0:164 offset1:166
	v_add_f32_e32 v65, v64, v65
	v_add_f32_e32 v64, v64, v64
	v_add_f32_e32 v109, v107, v51
	v_mov_b32_e32 v107, v65
	v_add_f32_e32 v64, v108, v106
	v_add_f32_e32 v65, v109, v107
	ds_read2_b64 v[104:107], v145 offset0:168 offset1:170
	v_add_f32_e32 v65, v64, v65
	v_add_f32_e32 v64, v64, v64
	s_waitcnt lgkmcnt(2)
	v_mfma_f32_32x32x16_bf16 v[18:33], v[136:139], v[110:113], v[18:33]
	ds_read2_b64 v[110:113], v144 offset0:132 offset1:134
	v_add_f32_e32 v57, v140, v53
	v_mov_b32_e32 v53, v65
	v_add_f32_e64 v52, v56, v52
	v_add_f32_e64 v53, v57, v53
	v_add_f32_e32 v63, v55, v39
	v_add_f32_e32 v53, v52, v53
	v_add_f32_e32 v52, v52, v52
	v_add_f32_e32 v51, v61, v41
	s_waitcnt lgkmcnt(0)
	v_mfma_f32_32x32x16_bf16 v[2:17], v[110:113], v[114:117], v[2:17]
	ds_read2_b64 v[110:113], v144 offset0:136 offset1:138
	v_mov_b32_e32 v61, v53
	v_add_f32_e64 v52, v62, v60
	v_add_f32_e64 v53, v63, v61
	ds_read2_b64 v[60:63], v144 offset0:140 offset1:142
	v_add_f32_e32 v53, v52, v53
	v_add_f32_e32 v52, v52, v52
	v_mov_b32_e32 v47, v53
	v_add_f32_e32 v46, v50, v46
	v_add_f32_e32 v47, v51, v47
	v_mfma_f32_32x32x16_bf16 v[18:33], v[132:135], v[114:117], v[18:33]
	ds_read2_b64 v[50:53], v145 offset0:172 offset1:174
	v_add_f32_e32 v47, v46, v47
	v_add_f32_e32 v46, v46, v46
	v_add_f32_e32 v59, v59, v43
	v_mov_b32_e32 v55, v47
	v_add_f32_e32 v46, v58, v54
	v_add_f32_e32 v47, v59, v55
	v_add_f32_e32 v43, v141, v45
	v_add_f32_e32 v47, v46, v47
	v_add_f32_e32 v46, v46, v46
	s_waitcnt lgkmcnt(2)
	v_mfma_f32_32x32x16_bf16 v[2:17], v[110:113], v[128:131], v[2:17]
	v_mov_b32_e32 v41, v47
	v_add_f32_e64 v40, v42, v40
	v_add_f32_e64 v41, v43, v41
	v_add_f32_e32 v49, v143, v142
	v_add_f32_e32 v41, v40, v41
	v_add_f32_e32 v40, v40, v40
	v_mov_b32_e32 v45, v41
	v_add_f32_e32 v40, v48, v44
	v_add_f32_e32 v41, v49, v45
	v_mfma_f32_32x32x16_bf16 v[18:33], v[104:107], v[128:131], v[18:33]
	v_add_f32_e32 v39, v40, v41
	v_fmac_f32_e32 v39, v119, v38
	v_mov_b32_e32 v104, v127
	v_mov_b32_e32 v119, v39
	s_waitcnt lgkmcnt(1)
	v_mfma_f32_32x32x16_bf16 v[2:17], v[60:63], v[34:37], v[2:17]
	s_waitcnt lgkmcnt(0)
	v_mfma_f32_32x32x16_bf16 v[18:33], v[50:53], v[34:37], v[18:33]
	s_andn2_b64 vcc, exec, s[12:13]
	s_xor_b32 s22, s22, 1
	s_cbranch_vccnz .LBB0_4542

.LBB0_4586:
	v_max3_f32 v170, v50, v51, v52
	v_max3_f32 v171, v34, v35, v36
	v_and_b32_e32 v212, 64, v217
	v_max3_f32 v170, v170, v53, v54
	v_max3_f32 v171, v171, v37, v38
	v_add_u32_e32 v212, 64, v212
	v_max3_f32 v170, v170, v55, v56
	v_max3_f32 v171, v171, v39, v40
	ds_write_b128 v169, v[94:97]
	s_waitcnt vmcnt(6)
	ds_write_b128 v169, v[106:109] offset:1152
	s_waitcnt vmcnt(5)
	ds_write_b128 v169, v[122:125] offset:2304
	s_waitcnt vmcnt(4)
	ds_write_b128 v169, v[126:129] offset:3456
	s_waitcnt vmcnt(3)
	ds_write_b128 v169, v[130:133] offset:4608
	v_max3_f32 v170, v170, v57, v58
	v_max3_f32 v171, v171, v41, v42
	s_waitcnt vmcnt(2)
	ds_write_b128 v169, v[134:137] offset:5760
	s_waitcnt vmcnt(1)
	ds_write_b128 v169, v[138:141] offset:6912
	s_waitcnt vmcnt(0)
	ds_write_b128 v169, v[142:145] offset:8064
	v_max3_f32 v170, v170, v59, v60
	v_max3_f32 v171, v171, v43, v44
	s_waitcnt lgkmcnt(0)
	s_mov_b64 s[20:21], 0x480
	v_max3_f32 v170, v170, v61, v62
	v_max3_f32 v171, v171, v45, v46
	s_nop 0
	v_max3_f32 v170, v170, v63, v64
	v_max3_f32 v171, v171, v47, v48
	s_nop 0
	v_max3_f32 v170, v170, v171, v65
	v_xor_b32_e32 v171, 32, v217
	v_cmp_lt_i32_e32 vcc, v171, v212
	v_max_f32_e32 v170, v170, v49
	s_nop 1
	v_cndmask_b32_e32 v171, v217, v171, vcc
	v_lshlrev_b32_e32 v227, 2, v171
	ds_bpermute_b32 v171, v227, v170
	s_waitcnt lgkmcnt(0)
	v_max_f32_e32 v170, v170, v171
	s_nop 0
	v_max_f32_e32 v212, v228, v170
	s_nop 0
	v_sub_f32_e32 v34, v34, v212
	v_sub_f32_e32 v170, v228, v212
	v_exp_f32_e32 v228, v34
	v_sub_f32_e32 v34, v51, v212
	v_exp_f32_e32 v51, v34
	v_sub_f32_e32 v34, v35, v212
	v_exp_f32_e32 v35, v34
	v_sub_f32_e32 v34, v52, v212
	v_exp_f32_e32 v52, v34
	v_sub_f32_e32 v34, v36, v212
	v_exp_f32_e32 v36, v34
	v_sub_f32_e32 v34, v53, v212
	v_exp_f32_e32 v53, v34
	v_sub_f32_e32 v34, v37, v212
	v_exp_f32_e32 v37, v34
	v_sub_f32_e32 v34, v54, v212
	v_exp_f32_e32 v54, v34
	v_sub_f32_e32 v34, v38, v212
	v_exp_f32_e32 v38, v34
	v_sub_f32_e32 v34, v55, v212
	v_exp_f32_e32 v55, v34
	v_sub_f32_e32 v34, v39, v212
	v_exp_f32_e32 v39, v34
	v_sub_f32_e32 v34, v56, v212
	v_exp_f32_e32 v56, v34
	v_sub_f32_e32 v34, v40, v212
	v_exp_f32_e32 v40, v34
	v_sub_f32_e32 v34, v57, v212
	v_exp_f32_e32 v57, v34
	v_sub_f32_e32 v34, v41, v212
	v_exp_f32_e32 v41, v34
	v_sub_f32_e32 v34, v58, v212
	v_exp_f32_e32 v58, v34
	v_sub_f32_e32 v34, v42, v212
	v_exp_f32_e32 v42, v34
	v_sub_f32_e32 v34, v59, v212
	v_exp_f32_e32 v59, v34
	v_sub_f32_e32 v34, v43, v212
	v_exp_f32_e32 v43, v34
	v_sub_f32_e32 v34, v60, v212
	v_exp_f32_e32 v60, v34
	v_sub_f32_e32 v34, v44, v212
	v_exp_f32_e32 v44, v34
	v_sub_f32_e32 v34, v61, v212
	v_exp_f32_e32 v61, v34
	v_sub_f32_e32 v34, v45, v212
	v_exp_f32_e32 v45, v34
	v_sub_f32_e32 v34, v62, v212
	v_exp_f32_e32 v62, v34
	v_sub_f32_e32 v34, v46, v212
	v_exp_f32_e32 v46, v34
	v_sub_f32_e32 v34, v63, v212
	v_exp_f32_e32 v63, v34
	v_sub_f32_e32 v34, v47, v212
	v_exp_f32_e32 v47, v34
	v_sub_f32_e32 v34, v64, v212
	v_sub_f32_e32 v50, v50, v212
	v_exp_f32_e32 v64, v34
	v_sub_f32_e32 v34, v48, v212
	v_sub_f32_e32 v65, v65, v212
	v_sub_f32_e32 v49, v49, v212
	v_exp_f32_e32 v50, v50
	v_exp_f32_e32 v48, v34
	v_exp_f32_e32 v34, v170
	v_exp_f32_e32 v65, v65
	v_exp_f32_e32 v49, v49
	v_cvt_pk_bf16_f32 v230, v50, v51
	v_cvt_pk_bf16_f32 v231, v52, v53
	v_cvt_pk_bf16_f32 v232, v54, v55
	v_cvt_pk_bf16_f32 v233, v56, v57
	v_cvt_pk_bf16_f32 v234, v58, v59
	v_cvt_pk_bf16_f32 v235, v60, v61
	v_cvt_pk_bf16_f32 v236, v62, v63
	v_cvt_pk_bf16_f32 v237, v64, v65
	v_cvt_pk_bf16_f32 v238, v228, v35
	v_cvt_pk_bf16_f32 v239, v36, v37
	v_cvt_pk_bf16_f32 v240, v38, v39
	v_cvt_pk_bf16_f32 v241, v40, v41
	v_cvt_pk_bf16_f32 v242, v42, v43
	v_cvt_pk_bf16_f32 v243, v44, v45
	v_cvt_pk_bf16_f32 v244, v46, v47
	v_cvt_pk_bf16_f32 v245, v48, v49
	v_mov_b64_e32 v[170:171], v[218:219]
	v_mul_f32_e32 v16, v16, v34
	v_mul_f32_e32 v17, v17, v34
	v_cmp_ne_u64_e32 vcc, 0, v[170:171]
	v_lshl_add_u64 v[246:247], v[170:171], 0, s[20:21]
	v_lshl_add_u64 v[250:251], v[170:171], 0, 64
	v_cndmask_b32_e32 v248, -1, v170, vcc
	v_cmp_ne_u64_e32 vcc, 0, v[246:247]
	s_mov_b64 s[20:21], 0x4c0
	v_mul_f32_e32 v14, v14, v34
	v_mul_f32_e32 v15, v15, v34
	v_cndmask_b32_e32 v249, -1, v246, vcc
	v_cmp_ne_u64_e32 vcc, 0, v[250:251]
	ds_read_b64_tr_b16 v[246:247], v248
	ds_read_b64_tr_b16 v[248:249], v249
	v_cndmask_b32_e32 v252, -1, v250, vcc
	v_lshl_add_u64 v[250:251], v[170:171], 0, s[20:21]
	v_cmp_ne_u64_e32 vcc, 0, v[250:251]
	v_mul_f32_e32 v12, v12, v34
	v_mul_f32_e32 v13, v13, v34
	v_mul_f32_e32 v10, v10, v34
	v_mul_f32_e32 v11, v11, v34
	v_cndmask_b32_e32 v253, -1, v250, vcc
	ds_read_b64_tr_b16 v[250:251], v252
	ds_read_b64_tr_b16 v[252:253], v253
	v_mul_f32_e32 v8, v8, v34
	v_mul_f32_e32 v9, v9, v34
	v_mul_f32_e32 v6, v6, v34
	v_mul_f32_e32 v7, v7, v34
	v_mul_f32_e32 v4, v4, v34
	v_mul_f32_e32 v5, v5, v34
	v_mul_f32_e32 v2, v2, v34
	v_mul_f32_e32 v3, v3, v34
	v_mul_f32_e32 v32, v32, v34
	v_mul_f32_e32 v33, v33, v34
	v_mul_f32_e32 v30, v30, v34
	v_mul_f32_e32 v31, v31, v34
	v_mul_f32_e32 v28, v28, v34
	v_mul_f32_e32 v29, v29, v34
	v_mul_f32_e32 v26, v26, v34
	v_mul_f32_e32 v27, v27, v34
	v_mul_f32_e32 v24, v24, v34
	v_mul_f32_e32 v25, v25, v34
	v_mul_f32_e32 v22, v22, v34
	v_mul_f32_e32 v23, v23, v34
	v_mul_f32_e32 v20, v20, v34
	v_mul_f32_e32 v21, v21, v34
	v_mul_f32_e32 v18, v18, v34
	v_mul_f32_e32 v19, v19, v34
	s_waitcnt lgkmcnt(2)
	v_mfma_f32_32x32x16_bf16 v[2:17], v[246:249], v[230:233], v[2:17]
	s_mov_b64 s[20:21], 0xd80
	v_lshl_add_u64 v[246:247], v[170:171], 0, s[72:73]
	s_waitcnt lgkmcnt(0)
	v_mfma_f32_32x32x16_bf16 v[18:33], v[250:253], v[230:233], v[18:33]
	v_lshl_add_u64 v[230:231], v[170:171], 0, s[70:71]
	v_cmp_ne_u64_e32 vcc, 0, v[230:231]
	s_nop 1
	v_cndmask_b32_e32 v232, -1, v230, vcc
	v_lshl_add_u64 v[230:231], v[170:171], 0, s[20:21]
	v_cmp_ne_u64_e32 vcc, 0, v[230:231]
	s_mov_b64 s[20:21], 0xdc0
	s_nop 0
	v_cndmask_b32_e32 v233, -1, v230, vcc
	v_cmp_ne_u64_e32 vcc, 0, v[246:247]
	ds_read_b64_tr_b16 v[230:231], v232
	ds_read_b64_tr_b16 v[232:233], v233
	v_cndmask_b32_e32 v248, -1, v246, vcc
	v_lshl_add_u64 v[246:247], v[170:171], 0, s[20:21]
	v_cmp_ne_u64_e32 vcc, 0, v[246:247]
	s_waitcnt lgkmcnt(0)
	v_mfma_f32_32x32x16_bf16 v[2:17], v[230:233], v[234:237], v[2:17]
	v_cndmask_b32_e32 v249, -1, v246, vcc
	ds_read_b64_tr_b16 v[246:247], v248
	ds_read_b64_tr_b16 v[248:249], v249
	v_lshl_add_u64 v[230:231], v[170:171], 0, s[76:77]
	v_cmp_ne_u64_e32 vcc, 0, v[230:231]
	s_mov_b64 s[20:21], 0x1680
	s_nop 0
	v_cndmask_b32_e32 v232, -1, v230, vcc
	v_lshl_add_u64 v[230:231], v[170:171], 0, s[20:21]
	s_waitcnt lgkmcnt(0)
	v_mfma_f32_32x32x16_bf16 v[18:33], v[246:249], v[234:237], v[18:33]
	v_cmp_ne_u64_e32 vcc, 0, v[230:231]
	v_lshl_add_u64 v[234:235], v[170:171], 0, s[78:79]
	s_mov_b64 s[20:21], 0x16c0
	v_cndmask_b32_e32 v233, -1, v230, vcc
	v_cmp_ne_u64_e32 vcc, 0, v[234:235]
	ds_read_b64_tr_b16 v[230:231], v232
	ds_read_b64_tr_b16 v[232:233], v233
	v_cndmask_b32_e32 v236, -1, v234, vcc
	v_lshl_add_u64 v[234:235], v[170:171], 0, s[20:21]
	v_cmp_ne_u64_e32 vcc, 0, v[234:235]
	s_waitcnt lgkmcnt(0)
	v_mfma_f32_32x32x16_bf16 v[2:17], v[230:233], v[238:241], v[2:17]
	v_cndmask_b32_e32 v237, -1, v234, vcc
	ds_read_b64_tr_b16 v[234:235], v236
	ds_read_b64_tr_b16 v[236:237], v237
	v_lshl_add_u64 v[230:231], v[170:171], 0, s[84:85]
	v_cmp_ne_u64_e32 vcc, 0, v[230:231]
	s_mov_b64 s[20:21], 0x1f80
	s_nop 0
	v_cndmask_b32_e32 v232, -1, v230, vcc
	v_lshl_add_u64 v[230:231], v[170:171], 0, s[20:21]
	s_waitcnt lgkmcnt(0)
	v_mfma_f32_32x32x16_bf16 v[18:33], v[234:237], v[238:241], v[18:33]
	v_cmp_ne_u64_e32 vcc, 0, v[230:231]
	v_lshl_add_u64 v[234:235], v[170:171], 0, s[86:87]
	s_mov_b64 s[20:21], 0x1fc0
	v_cndmask_b32_e32 v233, -1, v230, vcc
	v_cmp_ne_u64_e32 vcc, 0, v[234:235]
	v_lshl_add_u64 v[170:171], v[170:171], 0, s[20:21]
	ds_read_b64_tr_b16 v[230:231], v232
	ds_read_b64_tr_b16 v[232:233], v233
	v_cndmask_b32_e32 v234, -1, v234, vcc
	v_cmp_ne_u64_e32 vcc, 0, v[170:171]
	s_waitcnt lgkmcnt(0)
	v_mfma_f32_32x32x16_bf16 v[2:17], v[230:233], v[242:245], v[2:17]
	v_cndmask_b32_e32 v170, -1, v170, vcc
	ds_read_b64_tr_b16 v[234:235], v234
	ds_read_b64_tr_b16 v[236:237], v170
	s_andn2_b64 vcc, exec, s[12:13]
	s_waitcnt lgkmcnt(0)
	v_mfma_f32_32x32x16_bf16 v[18:33], v[234:237], v[242:245], v[18:33]
	s_waitcnt lgkmcnt(0)
	s_cbranch_vccnz .LBB0_4588
	v_lshl_add_u64 v[138:139], v[182:183], 0, s[10:11]
	v_add_co_u32_e32 v94, vcc, 0xe078000, v138
	s_nop 1
	v_addc_co_u32_e32 v95, vcc, 0, v139, vcc
	v_add_co_u32_e32 v106, vcc, 0xe087000, v138
	s_nop 1
	v_addc_co_u32_e32 v107, vcc, 0, v139, vcc
	v_add_co_u32_e32 v122, vcc, 0xe096000, v138
	global_load_dwordx4 v[94:97], v[94:95], off offset:2944
	s_nop 0
	global_load_dwordx4 v[106:109], v[106:107], off offset:2944
	v_addc_co_u32_e32 v123, vcc, 0, v139, vcc
	v_add_co_u32_e32 v126, vcc, 0xe0a5000, v138
	s_nop 1
	v_addc_co_u32_e32 v127, vcc, 0, v139, vcc
	v_add_co_u32_e32 v130, vcc, 0xe0b4000, v138
	global_load_dwordx4 v[122:125], v[122:123], off offset:2944
	s_nop 0
	global_load_dwordx4 v[126:129], v[126:127], off offset:2944
	v_addc_co_u32_e32 v131, vcc, 0, v139, vcc
	v_add_co_u32_e32 v134, vcc, 0xe0c3000, v138
	s_nop 1
	v_addc_co_u32_e32 v135, vcc, 0, v139, vcc
	v_add_co_u32_e32 v140, vcc, 0xe0d2000, v138
	global_load_dwordx4 v[130:133], v[130:131], off offset:2944
	s_nop 0
	global_load_dwordx4 v[134:137], v[134:135], off offset:2944
	v_addc_co_u32_e32 v141, vcc, 0, v139, vcc
	v_add_co_u32_e32 v142, vcc, 0xe0e1000, v138
	s_nop 1
	v_addc_co_u32_e32 v143, vcc, 0, v139, vcc
	global_load_dwordx4 v[138:141], v[140:141], off offset:2944
	s_nop 0
	global_load_dwordx4 v[142:145], v[142:143], off offset:2944

.LBB0_4603:
	v_max3_f32 v99, v34, v35, v36
	v_max3_f32 v100, v50, v51, v52
	v_and_b32_e32 v101, 64, v217
	v_max3_f32 v99, v99, v37, v38
	v_max3_f32 v100, v100, v53, v54
	v_add_u32_e32 v101, 64, v101
	v_max3_f32 v99, v99, v39, v40
	v_max3_f32 v100, v100, v55, v56
	s_nop 0
	v_max3_f32 v99, v99, v41, v42
	v_max3_f32 v100, v100, v57, v58
	s_nop 0
	v_max3_f32 v99, v99, v43, v44
	v_max3_f32 v100, v100, v59, v60
	s_nop 0
	v_max3_f32 v99, v99, v45, v46
	v_max3_f32 v100, v100, v61, v62
	s_nop 0
	v_max3_f32 v99, v99, v47, v48
	v_max3_f32 v100, v100, v63, v64
	s_nop 0
	v_max3_f32 v99, v99, v100, v49
	v_xor_b32_e32 v100, 32, v217
	v_cmp_lt_i32_e32 vcc, v100, v101
	v_max_f32_e32 v99, v99, v65
	s_nop 1
	v_cndmask_b32_e32 v100, v217, v100, vcc
	v_lshlrev_b32_e32 v100, 2, v100
	ds_bpermute_b32 v100, v100, v99
	s_waitcnt lgkmcnt(0)
	v_max_f32_e32 v99, v99, v100
	s_nop 0
	v_max_f32_e32 v109, v98, v99
	s_nop 0
	v_cmp_neq_f32_e32 vcc, s39, v109
	s_nop 1
	v_cndmask_b32_e32 v99, 0, v109, vcc
	v_sub_f32_e32 v34, v34, v99
	v_exp_f32_e32 v130, v34
	v_sub_f32_e32 v34, v50, v99
	v_exp_f32_e32 v131, v34
	v_sub_f32_e32 v34, v35, v99
	v_exp_f32_e32 v50, v34
	v_sub_f32_e32 v34, v51, v99
	v_exp_f32_e32 v148, v34
	v_sub_f32_e32 v34, v36, v99
	v_exp_f32_e32 v35, v34
	v_sub_f32_e32 v34, v52, v99
	v_exp_f32_e32 v132, v34
	v_sub_f32_e32 v34, v37, v99
	v_sub_f32_e32 v101, v98, v99
	v_exp_f32_e32 v98, v34
	v_sub_f32_e32 v34, v53, v99
	v_exp_f32_e32 v100, v34
	v_sub_f32_e32 v34, v38, v99
	v_exp_f32_e32 v37, v34
	v_sub_f32_e32 v34, v54, v99
	v_sub_f32_e32 v38, v40, v99
	v_exp_f32_e32 v53, v34
	v_sub_f32_e32 v34, v39, v99
	v_exp_f32_e32 v39, v38
	v_sub_f32_e32 v38, v56, v99
	v_sub_f32_e32 v36, v55, v99
	v_exp_f32_e32 v55, v38
	v_sub_f32_e32 v38, v41, v99
	v_exp_f32_e32 v40, v38
	v_sub_f32_e32 v38, v57, v99
	v_exp_f32_e32 v54, v38
	v_sub_f32_e32 v38, v42, v99
	v_exp_f32_e32 v57, v38
	v_sub_f32_e32 v38, v58, v99
	v_exp_f32_e32 v133, v38
	v_sub_f32_e32 v38, v43, v99
	v_exp_f32_e32 v52, v38
	v_sub_f32_e32 v38, v59, v99
	v_exp_f32_e32 v56, v38
	v_sub_f32_e32 v38, v44, v99
	v_exp_f32_e32 v43, v38
	v_sub_f32_e32 v38, v60, v99
	v_exp_f32_e32 v59, v38
	v_sub_f32_e32 v38, v45, v99
	v_exp_f32_e32 v58, v38
	v_sub_f32_e32 v38, v61, v99
	v_exp_f32_e32 v60, v38
	v_sub_f32_e32 v38, v46, v99
	v_sub_f32_e32 v41, v63, v99
	v_exp_f32_e32 v45, v38
	v_sub_f32_e32 v38, v62, v99
	v_exp_f32_e32 v42, v41
	v_sub_f32_e32 v41, v48, v99
	v_exp_f32_e32 v61, v38
	v_sub_f32_e32 v38, v47, v99
	v_exp_f32_e32 v47, v41
	v_sub_f32_e32 v41, v64, v99
	v_exp_f32_e32 v134, v41
	v_sub_f32_e32 v41, v49, v99
	v_exp_f32_e32 v46, v41
	v_sub_f32_e32 v41, v65, v99
	v_exp_f32_e32 v48, v41
	v_lshlrev_b32_e32 v41, 1, v154
	v_add3_u32 v41, s12, v103, v41
	v_add_u32_e32 v49, 0x2000, v41
	v_exp_f32_e32 v34, v34
	v_exp_f32_e32 v36, v36
	v_exp_f32_e32 v38, v38
	v_cvt_pk_bf16_f32 v62, v130, v50
	v_cvt_pk_bf16_f32 v63, v35, v98
	v_cvt_pk_bf16_f32 v64, v37, v34
	v_cvt_pk_bf16_f32 v65, v39, v40
	v_cvt_pk_bf16_f32 v110, v57, v52
	v_cvt_pk_bf16_f32 v111, v43, v58
	v_cvt_pk_bf16_f32 v112, v45, v38
	v_cvt_pk_bf16_f32 v113, v47, v46
	v_cvt_pk_bf16_f32 v114, v131, v148
	v_cvt_pk_bf16_f32 v115, v132, v100
	v_cvt_pk_bf16_f32 v116, v53, v36
	v_cvt_pk_bf16_f32 v117, v55, v54
	v_cvt_pk_bf16_f32 v118, v133, v56
	v_cvt_pk_bf16_f32 v119, v59, v60
	v_cvt_pk_bf16_f32 v120, v61, v42
	v_cvt_pk_bf16_f32 v121, v134, v48
	ds_read2_b64 v[122:125], v49 offset0:128 offset1:130
	v_add_u32_e32 v135, 0x3000, v41
	ds_read2_b64 v[126:129], v135 offset0:160 offset1:162
	v_exp_f32_e32 v44, v101
	v_add_f32_e32 v51, v130, v131
	v_add_f32_e32 v50, v50, v148
	v_add_f32_e32 v51, v51, v149
	v_add_f32_e32 v99, v35, v132
	v_mul_f32_e32 v32, v32, v44
	v_mul_f32_e32 v33, v33, v44
	v_mul_f32_e32 v30, v30, v44
	v_mul_f32_e32 v31, v31, v44
	v_mul_f32_e32 v28, v28, v44
	v_mul_f32_e32 v29, v29, v44
	v_mul_f32_e32 v26, v26, v44
	v_mul_f32_e32 v27, v27, v44
	v_mul_f32_e32 v24, v24, v44
	v_mul_f32_e32 v25, v25, v44
	v_mul_f32_e32 v22, v22, v44
	v_mul_f32_e32 v23, v23, v44
	v_mul_f32_e32 v20, v20, v44
	v_mul_f32_e32 v21, v21, v44
	v_mul_f32_e32 v18, v18, v44
	v_mul_f32_e32 v19, v19, v44
	v_mul_f32_e32 v16, v16, v44
	v_mul_f32_e32 v17, v17, v44
	v_mul_f32_e32 v14, v14, v44
	v_mul_f32_e32 v15, v15, v44
	s_waitcnt lgkmcnt(1)
	v_mfma_f32_32x32x16_bf16 v[18:33], v[122:125], v[62:65], v[18:33]
	v_mul_f32_e64 v12, v12, v44
	v_mul_f32_e64 v13, v13, v44
	v_mul_f32_e64 v10, v10, v44
	v_mul_f32_e64 v11, v11, v44
	v_mul_f32_e64 v8, v8, v44
	v_mul_f32_e64 v9, v9, v44
	v_mul_f32_e32 v6, v6, v44
	v_mul_f32_e32 v7, v7, v44
	v_mul_f32_e32 v4, v4, v44
	v_mul_f32_e32 v5, v5, v44
	v_mul_f32_e32 v2, v2, v44
	v_mul_f32_e32 v3, v3, v44
	v_add_f32_e32 v51, v50, v51
	v_add_f32_e32 v50, v50, v50
	v_mov_b32_e32 v101, v51
	s_waitcnt lgkmcnt(0)
	v_mfma_f32_32x32x16_bf16 v[2:17], v[126:129], v[62:65], v[2:17]
	ds_read2_b64 v[62:65], v49 offset0:132 offset1:134
	ds_read2_b64 v[122:125], v135 offset0:164 offset1:166
	v_add_f32_e64 v50, v98, v100
	v_add_f32_e64 v51, v99, v101
	ds_read2_b64 v[98:101], v135 offset0:168 offset1:170
	v_add_f32_e32 v51, v50, v51
	v_add_f32_e32 v50, v50, v50
	v_add_f32_e32 v35, v37, v53
	v_mov_b32_e32 v37, v51
	v_add_f32_e32 v34, v34, v36
	v_add_f32_e32 v35, v35, v37
	s_waitcnt lgkmcnt(2)
	v_mfma_f32_32x32x16_bf16 v[18:33], v[62:65], v[110:113], v[18:33]
	ds_read2_b64 v[62:65], v49 offset0:136 offset1:138
	v_add_f32_e32 v35, v34, v35
	v_add_f32_e32 v34, v34, v34
	v_add_f32_e32 v41, v39, v55
	v_mov_b32_e32 v55, v35
	v_add_f32_e32 v40, v40, v54
	v_add_f32_e32 v41, v41, v55
	v_add_f32_e32 v53, v57, v133
	v_add_f32_e32 v41, v40, v41
	v_add_f32_e32 v40, v40, v40
	s_waitcnt lgkmcnt(2)
	v_mfma_f32_32x32x16_bf16 v[2:17], v[122:125], v[110:113], v[2:17]
	ds_read2_b64 v[34:37], v49 offset0:140 offset1:142
	v_mov_b32_e32 v57, v41
	v_add_f32_e64 v40, v52, v56
	v_add_f32_e64 v41, v53, v57
	ds_read2_b64 v[50:53], v135 offset0:172 offset1:174
	v_add_f32_e32 v41, v40, v41
	v_add_f32_e32 v40, v40, v40
	v_add_f32_e32 v59, v43, v59
	v_add_f32_e32 v39, v45, v61
	s_waitcnt lgkmcnt(2)
	v_mfma_f32_32x32x16_bf16 v[18:33], v[62:65], v[114:117], v[18:33]
	v_mov_b32_e32 v61, v41
	v_add_f32_e64 v40, v58, v60
	v_add_f32_e64 v41, v59, v61
	v_add_f32_e32 v47, v47, v134
	v_mfma_f32_32x32x16_bf16 v[2:17], v[98:101], v[114:117], v[2:17]
	v_mov_b32_e32 v98, v109
	s_waitcnt lgkmcnt(1)
	v_mfma_f32_32x32x16_bf16 v[18:33], v[34:37], v[118:121], v[18:33]
	v_add_f32_e64 v34, v40, v40
	v_add_f32_e64 v35, v40, v41
	v_mov_b32_e32 v43, v35
	v_add_f32_e64 v34, v38, v42
	v_add_f32_e64 v35, v39, v43
	v_add_f32_e32 v35, v34, v35
	v_add_f32_e32 v34, v34, v34
	v_mov_b32_e32 v49, v35
	v_add_f32_e32 v34, v46, v48
	v_add_f32_e32 v35, v47, v49
	s_waitcnt lgkmcnt(0)
	v_mfma_f32_32x32x16_bf16 v[2:17], v[50:53], v[118:121], v[2:17]
	v_add_f32_e32 v34, v34, v35
	v_fmac_f32_e32 v34, v108, v44
	v_mov_b32_e32 v108, v34
	s_andn2_b64 vcc, exec, s[6:7]
	s_xor_b32 s8, s8, 1
	s_cbranch_vccnz .LBB0_4596

.LBB0_4605:
	v_and_b32_e32 v35, 64, v217
	v_xor_b32_e32 v34, 32, v217
	v_add_u32_e32 v35, 64, v35
	v_cmp_lt_i32_e32 vcc, v34, v35
	v_lshl_add_u32 v36, v223, 1, v223
	v_mov_b32_e32 v155, v149
	v_cndmask_b32_e32 v34, v217, v34, vcc
	v_lshlrev_b32_e32 v34, 2, v34
	ds_bpermute_b32 v34, v34, v108
	v_cmp_lt_i32_e32 vcc, -1, v221
	s_waitcnt lgkmcnt(0)
	v_add_f32_e32 v34, v108, v34
	s_and_saveexec_b64 s[6:7], vcc
	s_cbranch_execz .LBB0_4610
	v_mov_b64_e32 v[38:39], s[62:63]
	s_movk_i32 s4, 0x110
	v_mad_i64_i32 v[38:39], s[4:5], v36, s4, v[38:39]
	global_load_dwordx2 v[70:71], v[38:39], off offset:256
	s_waitcnt vmcnt(4)
	v_lshl_add_u64 v[66:67], v[154:155], 2, v[38:39]
	global_load_dwordx4 v[38:41], v[66:67], off offset:128
	global_load_dwordx4 v[42:45], v[66:67], off offset:32
	global_load_dwordx4 v[46:49], v[66:67], off offset:160
	global_load_dwordx4 v[50:53], v[66:67], off offset:64
	global_load_dwordx4 v[54:57], v[66:67], off offset:192
	global_load_dwordx4 v[58:61], v[66:67], off offset:96
	global_load_dwordx4 v[62:65], v[66:67], off offset:224
	s_nop 0
	global_load_dwordx4 v[66:69], v[66:67], off
	s_waitcnt vmcnt(8)
	v_max_f32_e32 v37, v98, v70
	s_nop 0
	v_sub_f32_e32 v35, v98, v37
	v_mov_b32_e32 v98, v37
	v_sub_f32_e32 v72, v70, v37
	v_exp_f32_e32 v70, v35
	v_exp_f32_e32 v72, v72
	v_mov_b32_e32 v35, v71
	v_mul_f32_e32 v18, v18, v70
	v_mul_f32_e32 v19, v19, v70
	v_mul_f32_e32 v20, v20, v70
	v_mul_f32_e32 v21, v21, v70
	s_waitcnt vmcnt(6)
	v_mul_f32_e32 v42, v72, v42
	v_mul_f32_e32 v43, v72, v43
	s_waitcnt vmcnt(2)
	v_mul_f32_e32 v74, v72, v60
	s_waitcnt vmcnt(1)
	v_mul_f32_e32 v76, v72, v64
	v_mov_b32_e32 v60, v33
	v_mov_b32_e32 v71, v72
	v_mov_b32_e32 v64, v17
	v_mul_f32_e32 v60, v60, v70
	v_mul_f32_e32 v61, v61, v71
	v_fma_f32 v22, v22, v70, v42
	v_fma_f32 v23, v23, v70, v43
	v_mul_f32_e32 v42, v64, v70
	v_mul_f32_e32 v43, v65, v71
	v_mul_f32_e32 v38, v72, v38
	v_mul_f32_e32 v39, v72, v39
	v_mul_f32_e32 v40, v72, v40
	v_mul_f32_e32 v41, v72, v41
	v_mul_f32_e32 v46, v72, v46
	v_mul_f32_e32 v47, v72, v47
	v_mul_f32_e32 v44, v72, v44
	v_mul_f32_e32 v45, v72, v45
	v_mul_f32_e32 v48, v72, v48
	v_mul_f32_e32 v49, v72, v49
	v_mul_f32_e32 v50, v72, v50
	v_mul_f32_e32 v51, v72, v51
	v_mul_f32_e32 v54, v72, v54
	v_mul_f32_e32 v55, v72, v55
	v_mul_f32_e32 v52, v72, v52
	v_mul_f32_e32 v53, v72, v53
	v_mul_f32_e32 v56, v72, v56
	v_mul_f32_e32 v57, v72, v57
	v_mul_f32_e32 v58, v72, v58
	v_mul_f32_e32 v59, v72, v59
	v_mul_f32_e32 v62, v72, v62
	v_mul_f32_e32 v63, v72, v63
	v_mul_f32_e32 v32, v32, v70
	v_mul_f32_e32 v16, v16, v70
	v_mul_f32_e32 v34, v34, v70
	v_mul_f32_e32 v35, v35, v71
	v_mov_b32_e32 v33, v60
	v_mov_b32_e32 v75, v61
	v_mov_b32_e32 v17, v42
	v_mov_b32_e32 v77, v43
	s_waitcnt vmcnt(0)
	v_fma_f32 v18, v72, v66, v18
	v_fma_f32 v19, v72, v67, v19
	v_fma_f32 v20, v72, v68, v20
	v_fma_f32 v21, v72, v69, v21
	v_fma_f32 v24, v24, v70, v44
	v_fma_f32 v25, v25, v70, v45
	v_fma_f32 v26, v26, v70, v50
	v_fma_f32 v27, v27, v70, v51
	v_fma_f32 v28, v28, v70, v52
	v_fma_f32 v29, v29, v70, v53
	v_fma_f32 v30, v30, v70, v58
	v_fma_f32 v31, v31, v70, v59
	v_fma_f32 v2, v2, v70, v38
	v_fma_f32 v3, v3, v70, v39
	v_fma_f32 v4, v4, v70, v40
	v_fma_f32 v5, v5, v70, v41
	v_fma_f32 v6, v6, v70, v46
	v_fma_f32 v7, v7, v70, v47
	v_fma_f32 v8, v8, v70, v48
	v_fma_f32 v9, v9, v70, v49
	v_fma_f32 v10, v10, v70, v54
	v_fma_f32 v11, v11, v70, v55
	v_fma_f32 v12, v12, v70, v56
	v_fma_f32 v13, v13, v70, v57
	v_fma_f32 v14, v14, v70, v62
	v_fma_f32 v15, v15, v70, v63
	v_add_f32_e32 v34, v34, v35
	v_add_f32_e32 v32, v32, v74
	v_add_f32_e32 v33, v33, v75
	v_add_f32_e32 v16, v16, v76
	v_add_f32_e32 v17, v17, v77
	s_or_b64 exec, exec, s[6:7]
	v_cmp_lt_i32_e32 vcc, -1, v220
	s_and_saveexec_b64 s[6:7], vcc
	s_cbranch_execnz .LBB0_4611

.LBB0_4608:
	v_add_u32_e32 v35, 2, v36
	v_mov_b64_e32 v[36:37], s[62:63]
	s_movk_i32 s4, 0x110
	v_mad_i64_i32 v[36:37], s[4:5], v35, s4, v[36:37]
	global_load_dwordx2 v[68:69], v[36:37], off offset:256
	v_lshl_add_u64 v[64:65], v[154:155], 2, v[36:37]
	global_load_dwordx4 v[36:39], v[64:65], off offset:128
	global_load_dwordx4 v[40:43], v[64:65], off offset:32
	global_load_dwordx4 v[44:47], v[64:65], off offset:160
	global_load_dwordx4 v[48:51], v[64:65], off offset:64
	global_load_dwordx4 v[52:55], v[64:65], off offset:192
	global_load_dwordx4 v[56:59], v[64:65], off offset:96
	global_load_dwordx4 v[60:63], v[64:65], off offset:224
	s_nop 0
	global_load_dwordx4 v[64:67], v[64:65], off
	s_waitcnt vmcnt(8)
	v_max_f32_e32 v35, v98, v68
	s_nop 0
	v_sub_f32_e32 v70, v98, v35
	v_sub_f32_e32 v35, v68, v35
	v_exp_f32_e32 v68, v70
	v_exp_f32_e32 v70, v35
	v_mov_b32_e32 v35, v69
	v_mul_f32_e32 v18, v18, v68
	v_mul_f32_e32 v19, v19, v68
	v_mul_f32_e32 v20, v20, v68
	v_mul_f32_e32 v21, v21, v68
	s_waitcnt vmcnt(6)
	v_mul_f32_e32 v40, v70, v40
	v_mul_f32_e32 v41, v70, v41
	s_waitcnt vmcnt(2)
	v_mul_f32_e32 v72, v70, v58
	s_waitcnt vmcnt(1)
	v_mul_f32_e32 v74, v70, v62
	v_mov_b32_e32 v58, v33
	v_mov_b32_e32 v69, v70
	v_mov_b32_e32 v62, v17
	v_mul_f32_e32 v58, v58, v68
	v_mul_f32_e32 v59, v59, v69
	v_fma_f32 v22, v22, v68, v40
	v_fma_f32 v23, v23, v68, v41
	v_mul_f32_e32 v40, v62, v68
	v_mul_f32_e32 v41, v63, v69
	v_mul_f32_e32 v36, v70, v36
	v_mul_f32_e32 v37, v70, v37
	v_mul_f32_e32 v38, v70, v38
	v_mul_f32_e32 v39, v70, v39
	v_mul_f32_e32 v44, v70, v44
	v_mul_f32_e32 v45, v70, v45
	v_mul_f32_e32 v42, v70, v42
	v_mul_f32_e32 v43, v70, v43
	v_mul_f32_e32 v46, v70, v46
	v_mul_f32_e32 v47, v70, v47
	v_mul_f32_e32 v48, v70, v48
	v_mul_f32_e32 v49, v70, v49
	v_mul_f32_e32 v52, v70, v52
	v_mul_f32_e32 v53, v70, v53
	v_mul_f32_e32 v50, v70, v50
	v_mul_f32_e32 v51, v70, v51
	v_mul_f32_e32 v54, v70, v54
	v_mul_f32_e32 v55, v70, v55
	v_mul_f32_e32 v56, v70, v56
	v_mul_f32_e32 v57, v70, v57
	v_mul_f32_e32 v60, v70, v60
	v_mul_f32_e32 v61, v70, v61
	v_mul_f32_e32 v32, v32, v68
	v_mul_f32_e32 v16, v16, v68
	v_mul_f32_e32 v34, v34, v68
	v_mul_f32_e32 v35, v35, v69
	v_mov_b32_e32 v33, v58
	v_mov_b32_e32 v73, v59
	v_mov_b32_e32 v17, v40
	v_mov_b32_e32 v75, v41
	s_waitcnt vmcnt(0)
	v_fma_f32 v18, v70, v64, v18
	v_fma_f32 v19, v70, v65, v19
	v_fma_f32 v20, v70, v66, v20
	v_fma_f32 v21, v70, v67, v21
	v_fma_f32 v24, v24, v68, v42
	v_fma_f32 v25, v25, v68, v43
	v_fma_f32 v26, v26, v68, v48
	v_fma_f32 v27, v27, v68, v49
	v_fma_f32 v28, v28, v68, v50
	v_fma_f32 v29, v29, v68, v51
	v_fma_f32 v30, v30, v68, v56
	v_fma_f32 v31, v31, v68, v57
	v_fma_f32 v2, v2, v68, v36
	v_fma_f32 v3, v3, v68, v37
	v_fma_f32 v4, v4, v68, v38
	v_fma_f32 v5, v5, v68, v39
	v_fma_f32 v6, v6, v68, v44
	v_fma_f32 v7, v7, v68, v45
	v_fma_f32 v8, v8, v68, v46
	v_fma_f32 v9, v9, v68, v47
	v_fma_f32 v10, v10, v68, v52
	v_fma_f32 v11, v11, v68, v53
	v_fma_f32 v12, v12, v68, v54
	v_fma_f32 v13, v13, v68, v55
	v_fma_f32 v14, v14, v68, v60
	v_fma_f32 v15, v15, v68, v61
	v_add_f32_e32 v32, v32, v72
	v_add_f32_e32 v33, v33, v73
	v_add_f32_e32 v16, v16, v74
	v_add_f32_e32 v17, v17, v75
	v_add_f32_e32 v34, v34, v35
